# gating: hoist unit-invariant LN gain/bias, b_s and W fragments, waits moved; attention loop: static s_setprio 1 for waves 4-7
# speedup vs baseline: 1.0486x; 1.0102x over previous
; #define DMA(t) do { const int t_ = (t) < NT ? (t) : NT - 1; const long off_ = (long)t_ * (KVBLK * LDK); \
;         __builtin_amdgcn_global_load_lds((const unsigned*)(kptr + off_), (LAS unsigned*)(ldsK + SLOT(t)), 16, 0, 0); \
;         __builtin_amdgcn_global_load_lds((const unsigned*)(vptr + off_), (LAS unsigned*)(ldsV + SLOT(t)), 16, 0, 0); } while (0)
; #define WBAR(N) asm volatile("s_waitcnt vmcnt(" #N ") lgkmcnt(0)\n\ts_barrier" ::: "memory")
; __device__ __forceinline__ void attn_body(const bf16* __restrict__ Qb, const bf16* __restrict__ Kh, const bf16* __restrict__ Vh, bf16* __restrict__ Ob, int seq, float m0l2, char* lds, bool pre, bool post) {
;     ...
;     if (!pre) { DMA(0); DMA(1); } DMA(2); WBAR(2);
;     qkt(pA0, pA1, K_lds, qr, negm, r32, hi); partialSM(pA0);
;     int j = 1;
;     for (; j + 4 < NT; j += 2) {
.LBB0_26:
	s_lshl_b32 s25, s7, 6
	s_cmp_lg_u32 0, -1
	s_cselect_b32 s39, 0, 0
	v_lshl_add_u64 v[16:17], v[132:133], 0, s[82:83]
	s_add_i32 m0, s26, 0xc000
	v_lshlrev_b32_e32 v39, 8, v150
	global_load_lds_dwordx4 v[16:17], off
	v_lshl_add_u64 v[16:17], v[134:135], 0, s[82:83]
	s_add_i32 m0, s26, 0x4000
	s_movk_i32 s7, 0xc0
	global_load_lds_dwordx4 v[16:17], off
	v_lshlrev_b32_e32 v16, 4, v150
	v_and_b32_e32 v80, 0xf0, v16
	v_lshrrev_b32_e32 v39, 4, v150
	v_lshlrev_b32_e32 v39, 11, v39
	v_lshl_add_u32 v39, v130, 4, v39
	v_add_u32_e32 v39, v39, v80
	v_mov_b32_e32 v163, v39
	s_waitcnt vmcnt(2) lgkmcnt(0)
	s_barrier
	v_add_u32_e32 v154, 0, v163
	ds_read_b128 v[40:43], v154 offset:32768
	v_or_b32_e32 v16, 0x80, v130
	v_add_u32_e32 v164, 4096, v39
	v_add_u32_e32 v162, 0, v164
	ds_read_b128 v[44:47], v162 offset:32768
	s_waitcnt vmcnt(0) lgkmcnt(0)
	v_mfma_f32_32x32x16_bf16 v[16:31], v[40:43], v[124:127], v[48:63]
	v_or_b32_e32 v40, 32, v130
	v_add_u32_e32 v165, 512, v39
	v_add_u32_e32 v153, 0, v165
	ds_read_b128 v[40:43], v153 offset:32768
	s_add_i32 s38, s38, s37
	v_mfma_f32_32x32x16_bf16 v[64:79], v[44:47], v[124:127], v[48:63]
	v_or_b32_e32 v44, 0xa0, v130
	v_add_u32_e32 v166, 4608, v39
	v_add_u32_e32 v157, 0, v166
	ds_read_b128 v[44:47], v157 offset:32768
	s_waitcnt lgkmcnt(1)
	v_mfma_f32_32x32x16_bf16 v[16:31], v[40:43], v[120:123], v[16:31]
	v_or_b32_e32 v40, 64, v130
	v_add_u32_e32 v167, 1024, v39
	v_add_u32_e32 v156, 0, v167
	ds_read_b128 v[40:43], v156 offset:32768
	s_waitcnt lgkmcnt(1)
	v_mfma_f32_32x32x16_bf16 v[64:79], v[44:47], v[120:123], v[64:79]
	v_or_b32_e32 v44, 0xc0, v130
	v_add_u32_e32 v168, 5120, v39
	v_add_u32_e32 v158, 0, v168
	ds_read_b128 v[44:47], v158 offset:32768
	s_waitcnt lgkmcnt(1)
	v_mfma_f32_32x32x16_bf16 v[16:31], v[40:43], v[116:119], v[16:31]
	v_or_b32_e32 v40, 0x60, v130
	v_add_u32_e32 v169, 1536, v39
	v_add_u32_e32 v155, 0, v169
	ds_read_b128 v[40:43], v155 offset:32768
	s_waitcnt lgkmcnt(1)
	v_mfma_f32_32x32x16_bf16 v[64:79], v[44:47], v[116:119], v[64:79]
	v_or_b32_e32 v44, 0xe0, v130
	v_add_u32_e32 v170, 5632, v39
	v_add_u32_e32 v159, 0, v170
	ds_read_b128 v[44:47], v159 offset:32768
	v_lshlrev_b32_e32 v39, 1, v131
	v_and_b32_e32 v39, 32, v39
	v_and_or_b32 v38, v38, s7, v39
	s_waitcnt lgkmcnt(1)
	v_mfma_f32_32x32x16_bf16 v[16:31], v[40:43], v[112:115], v[16:31]
	v_lshlrev_b32_e32 v39, 5, v131
	v_and_b32_e32 v39, 0x400, v39
	v_or3_b32 v129, v38, v39, v35
	v_add_u32_e32 v172, s39, v129
	s_mov_b32 s7, -1
	s_nop 6
	v_exp_f32_e32 v183, v16
	s_waitcnt lgkmcnt(0)
	v_mfma_f32_32x32x16_bf16 v[64:79], v[44:47], v[112:115], v[64:79]
	v_exp_f32_e32 v188, v17
	v_mad_u64_u32 v[16:17], s[46:47], s27, v211, v[32:33]
	v_lshl_add_u64 v[16:17], v[16:17], 0, v[160:161]
	v_lshl_add_u64 v[140:141], s[28:29], 0, v[16:17]
	v_add3_u32 v16, s38, v37, v36
	v_ashrrev_i32_e32 v17, 31, v16
	v_exp_f32_e32 v185, v18
	v_exp_f32_e32 v187, v19
	v_exp_f32_e32 v184, v20
	v_exp_f32_e32 v186, v21
	v_exp_f32_e32 v181, v22
	v_exp_f32_e32 v182, v23
	v_exp_f32_e32 v178, v24
	v_exp_f32_e32 v180, v25
	v_exp_f32_e32 v176, v26
	v_exp_f32_e32 v179, v27
	v_exp_f32_e32 v175, v28
	v_exp_f32_e32 v177, v29
	v_exp_f32_e32 v173, v30
	v_exp_f32_e32 v174, v31
	v_lshlrev_b64 v[16:17], 8, v[16:17]
	v_mad_u64_u32 v[16:17], s[38:39], s27, v211, v[16:17]
	v_add_u32_e32 v18, v34, v35
	v_lshl_or_b32 v16, v18, 1, v16
	v_mov_b32_e32 v160, 0
	v_lshl_add_u64 v[142:143], s[28:29], 0, v[16:17]
	s_mov_b32 s27, 0x8000
	v_mov_b32_e32 v16, 0
	v_mov_b32_e32 v17, v160
	v_mov_b32_e32 v18, v160
	v_mov_b32_e32 v19, v160
	v_mov_b32_e32 v20, v160
	v_mov_b32_e32 v21, v160
	v_mov_b32_e32 v22, v160
	v_mov_b32_e32 v23, v160
	v_mov_b32_e32 v24, v160
	v_mov_b32_e32 v25, v160
	v_mov_b32_e32 v26, v160
	v_mov_b32_e32 v27, v160
	v_mov_b32_e32 v28, v160
	v_mov_b32_e32 v29, v160
	v_mov_b32_e32 v30, v160
	v_mov_b32_e32 v31, v160
	v_mov_b32_e32 v32, 0
	v_mov_b32_e32 v33, v160
	v_mov_b32_e32 v34, v160
	v_mov_b32_e32 v35, v160
	v_mov_b32_e32 v36, v160
	v_mov_b32_e32 v37, v160
	v_mov_b32_e32 v38, v160
	v_mov_b32_e32 v39, v160
	v_mov_b32_e32 v40, v160
	v_mov_b32_e32 v41, v160
	v_mov_b32_e32 v42, v160
	v_mov_b32_e32 v43, v160
	v_mov_b32_e32 v44, v160
	v_mov_b32_e32 v45, v160
	v_mov_b32_e32 v46, v160
	v_mov_b32_e32 v47, v160
	v_lshl_add_u64 v[140:141], v[140:141], 0, s[72:73]
	v_lshl_add_u64 v[142:143], v[142:143], 0, s[72:73]
	s_mov_b64 s[38:39], 0x10e06000
	s_mov_b64 s[46:47], 0x11686000
	s_mov_b64 s[62:63], 0x4000
	v_lshl_add_u64 v[140:141], v[140:141], 0, s[38:39]
	v_lshl_add_u64 v[142:143], v[142:143], 0, s[46:47]
	ds_read_b128 v[234:237], v163 offset:40960
	ds_read_b128 v[238:241], v165 offset:40960
	ds_read_b128 v[242:245], v167 offset:40960
	ds_read_b128 v[246:249], v169 offset:40960
	v_readfirstlane_b32 s37, v151
	s_nop 0
	s_cmp_ge_u32 s37, 4
	s_cbranch_scc0 .Lattn_prio_skip
	s_setprio 1
; __device__ __forceinline__ void qkt(f32x16& p0, f32x16& p1, const char* Ks, const bf16x8* qr, const f32x16& negm, int r32, int hi) {
; #pragma unroll
;     for (int d0 = 0; d0 < 4; ++d0) { const int cb = (d0 * 16 + hi * 8) * 2;
;         const bf16x8 b0 = *reinterpret_cast<const bf16x8*>(Ks + KSWZ(r32, cb));
;         const bf16x8 b1 = *reinterpret_cast<const bf16x8*>(Ks + KSWZ(r32, 128 + cb));
;         if (d0 == 0) { p0 = __builtin_amdgcn_mfma_f32_32x32x16_bf16(b0, qr[0], negm, 0, 0, 0); p1 = __builtin_amdgcn_mfma_f32_32x32x16_bf16(b1, qr[0], negm, 0, 0, 0); }
;         else { p0 = __builtin_amdgcn_mfma_f32_32x32x16_bf16(b0, qr[d0], p0, 0, 0, 0); p1 = __builtin_amdgcn_mfma_f32_32x32x16_bf16(b1, qr[d0], p1, 0, 0, 0); } }
; }
; __device__ __forceinline__ int v_st(int k, int c) { const int kk = (k & ~0xC) | ((k & 4) << 1) | ((k & 8) >> 1); return ((kk >> 3) * 2 + (c >> 5)) * 512 + ((kk & 7) * 32 + (c & 31)) * 2; }
; __device__ __forceinline__ int v_rd_base(int lane) { return (((lane & 3) << 3) | (((lane >> 2) & 3) << 6) | (((lane >> 4) & 1) << 5)) + ((lane >> 5) & 1) * 1024; }
; template <int OFF> __device__ __forceinline__ s16x4 tr_read(int vb) {
;     return __builtin_bit_cast(s16x4, __builtin_amdgcn_ds_read_tr16_b64_v4i16((LAS v4i16_t*)(unsigned)(vb + OFF)));
; }
; template <int D0> __device__ __forceinline__ void pv_one(f32x16& od, int vb, bf16x8 pa0, bf16x8 pa1, bf16x8 pa2, bf16x8 pa3) {
;     const s16x4 l0 = tr_read<v_rd_off(D0, 0, 0)>(vb), h0 = tr_read<v_rd_off(D0, 0, 1)>(vb), l1 = tr_read<v_rd_off(D0, 1, 0)>(vb), h1 = tr_read<v_rd_off(D0, 1, 1)>(vb);
;     const s16x4 l2 = tr_read<v_rd_off(D0, 2, 0)>(vb), h2 = tr_read<v_rd_off(D0, 2, 1)>(vb), l3 = tr_read<v_rd_off(D0, 3, 0)>(vb), h3 = tr_read<v_rd_off(D0, 3, 1)>(vb);
;     ...
;     od = __builtin_amdgcn_mfma_f32_32x32x16_bf16(pa0, PK(l0, h0), od, 0, 0, 0);
;     od = __builtin_amdgcn_mfma_f32_32x32x16_bf16(pa1, PK(l1, h1), od, 0, 0, 0);
; __device__ __forceinline__ void attn_body(const bf16* __restrict__ Qb, const bf16* __restrict__ Kh, const bf16* __restrict__ Vh, bf16* __restrict__ Ob, int seq, float m0l2, char* lds, bool pre, bool post) {
;     ...
;     if (!pre) { DMA(0); DMA(1); } DMA(2); WBAR(2);
;     qkt(pA0, pA1, K_lds, qr, negm, r32, hi); partialSM(pA0);
;     int j = 1;
;     for (; j + 4 < NT; j += 2) {
;         HALF(pB0, pB1, pA0, pA1, j, true);
;         HALF(pA0, pA1, pB0, pB1, j + 1, true);
;     }
.Lattn_prio_skip:
.LBB0_27:
	s_add_i32 m0, s26, 0xe000
	s_nop 0
	global_load_lds_dwordx4 v[140:141], off
	v_lshl_add_u64 v[140:141], v[140:141], 0, s[62:63]
	s_add_i32 m0, s26, 0x6000
	s_nop 0
	global_load_lds_dwordx4 v[142:143], off
	v_lshl_add_u64 v[142:143], v[142:143], 0, s[62:63]
	s_waitcnt lgkmcnt(3)
	v_mfma_f32_32x32x16_bf16 v[96:111], v[234:237], v[124:127], v[0:15]
	ds_read_b64_tr_b16 v[190:191], v172 offset:0
	ds_read_b64_tr_b16 v[192:193], v172 offset:256
	v_add_f32_e32 v189, v183, v188
	v_add_f32_e32 v189, v185, v189
	v_add_f32_e32 v189, v187, v189
	v_add_f32_e32 v189, v184, v189
	v_exp_f32_e32 v64, v64
	s_waitcnt lgkmcnt(4)
	v_mfma_f32_32x32x16_bf16 v[96:111], v[238:241], v[120:123], v[96:111]
	ds_read_b64_tr_b16 v[194:195], v172 offset:2048
	ds_read_b64_tr_b16 v[196:197], v172 offset:2304
	v_exp_f32_e32 v65, v65
	v_cvt_pk_bf16_f32 v48, v183, v188
	v_exp_f32_e32 v66, v66
	v_exp_f32_e32 v67, v67
	s_waitcnt lgkmcnt(5)
	v_mfma_f32_32x32x16_bf16 v[96:111], v[242:245], v[116:119], v[96:111]
	ds_read_b64_tr_b16 v[144:145], v172 offset:4096
	ds_read_b64_tr_b16 v[146:147], v172 offset:4352
	v_cvt_pk_bf16_f32 v49, v185, v187
	v_exp_f32_e32 v68, v68
	v_exp_f32_e32 v69, v69
	v_cvt_pk_bf16_f32 v50, v184, v186
	s_waitcnt lgkmcnt(6)
	v_mfma_f32_32x32x16_bf16 v[96:111], v[246:249], v[112:115], v[96:111]
	ds_read_b64_tr_b16 v[250:251], v172 offset:6144
	ds_read_b64_tr_b16 v[252:253], v172 offset:6400
	v_exp_f32_e32 v70, v70
	v_exp_f32_e32 v71, v71
	v_cvt_pk_bf16_f32 v51, v181, v182
	v_cvt_pk_bf16_f32 v52, v178, v180
	s_waitcnt lgkmcnt(6)
	v_mfma_f32_32x32x16_bf16 v[32:47], v[48:51], v[190:193], v[32:47]
	ds_read_b64_tr_b16 v[190:191], v172 offset:512
	ds_read_b64_tr_b16 v[192:193], v172 offset:768
	ds_read_b128 v[234:237], v164 offset:40960
	v_cvt_pk_bf16_f32 v53, v176, v179
	v_cvt_pk_bf16_f32 v54, v175, v177
	v_cvt_pk_bf16_f32 v55, v173, v174
	v_cvt_pk_bf16_f32 v56, v64, v65
	v_cvt_pk_bf16_f32 v57, v66, v67
	v_exp_f32_e32 v72, v72
	s_waitcnt lgkmcnt(7)
	v_mfma_f32_32x32x16_bf16 v[32:47], v[52:55], v[194:197], v[32:47]
	ds_read_b64_tr_b16 v[194:195], v172 offset:2560
	ds_read_b64_tr_b16 v[196:197], v172 offset:2816
	ds_read_b128 v[238:241], v166 offset:40960
	v_cvt_pk_bf16_f32 v58, v68, v69
	v_cvt_pk_bf16_f32 v59, v70, v71
	v_exp_f32_e32 v73, v73
	v_exp_f32_e32 v74, v74
	s_waitcnt lgkmcnt(4)
	v_mfma_f32_32x32x16_bf16 v[16:31], v[48:51], v[190:193], v[16:31]
	ds_read_b64_tr_b16 v[190:191], v172 offset:4608
	ds_read_b64_tr_b16 v[192:193], v172 offset:4864
	ds_read_b128 v[242:245], v168 offset:40960
	v_exp_f32_e32 v75, v75
	v_exp_f32_e32 v76, v76
	v_exp_f32_e32 v77, v77
	v_add_f32_e32 v189, v186, v189
	s_waitcnt lgkmcnt(4)
	v_mfma_f32_32x32x16_bf16 v[16:31], v[52:55], v[194:197], v[16:31]
	ds_read_b64_tr_b16 v[194:195], v172 offset:6656
	ds_read_b64_tr_b16 v[196:197], v172 offset:6912
	ds_read_b128 v[246:249], v170 offset:40960
	v_exp_f32_e32 v78, v78
	v_exp_f32_e32 v79, v79
	v_add_f32_e32 v189, v181, v189
	v_add_f32_e32 v189, v182, v189
	v_cvt_pk_bf16_f32 v60, v72, v73
	v_mfma_f32_32x32x16_bf16 v[32:47], v[56:59], v[144:147], v[32:47]
	v_cvt_pk_bf16_f32 v61, v74, v75
	v_cvt_pk_bf16_f32 v62, v76, v77
	v_cvt_pk_bf16_f32 v63, v78, v79
	v_add_f32_e32 v189, v178, v189
	v_add_f32_e32 v189, v180, v189
	v_add_f32_e32 v189, v176, v189
	v_add_f32_e32 v189, v179, v189
	v_mfma_f32_32x32x16_bf16 v[32:47], v[60:63], v[250:253], v[32:47]
	v_exp_f32_e32 v96, v96
	v_exp_f32_e32 v97, v97
	v_add_f32_e32 v189, v175, v189
	v_add_f32_e32 v189, v177, v189
	v_add_f32_e32 v189, v173, v189
	s_waitcnt lgkmcnt(4)
	v_mfma_f32_32x32x16_bf16 v[16:31], v[56:59], v[190:193], v[16:31]
	v_exp_f32_e32 v98, v98
	v_exp_f32_e32 v99, v99
	v_add_f32_e32 v189, v174, v189
	v_add_f32_e32 v189, v64, v189
	v_add_f32_e32 v189, v65, v189
	s_waitcnt lgkmcnt(1)
	v_mfma_f32_32x32x16_bf16 v[16:31], v[60:63], v[194:197], v[16:31]
	v_exp_f32_e32 v100, v100
	v_exp_f32_e32 v101, v101
	v_add_f32_e32 v189, v66, v189
	v_add_f32_e32 v189, v67, v189
	v_add_f32_e32 v189, v68, v189
	s_waitcnt vmcnt(2) lgkmcnt(0)
	s_barrier
	v_mfma_f32_32x32x16_bf16 v[80:95], v[234:237], v[124:127], v[0:15]
	ds_read_b128 v[234:237], v163 offset:49152
	v_exp_f32_e32 v102, v102
	v_exp_f32_e32 v103, v103
	v_add_f32_e32 v189, v69, v189
	v_add_f32_e32 v189, v70, v189
	v_add_f32_e32 v189, v71, v189
	v_mfma_f32_32x32x16_bf16 v[80:95], v[238:241], v[120:123], v[80:95]
	ds_read_b128 v[238:241], v165 offset:49152
	v_exp_f32_e32 v104, v104
	v_exp_f32_e32 v105, v105
	v_exp_f32_e32 v106, v106
	v_add_f32_e32 v189, v72, v189
	v_add_f32_e32 v189, v73, v189
	v_mfma_f32_32x32x16_bf16 v[80:95], v[242:245], v[116:119], v[80:95]
	ds_read_b128 v[242:245], v167 offset:49152
	v_exp_f32_e32 v107, v107
	v_exp_f32_e32 v108, v108
	v_exp_f32_e32 v109, v109
	v_add_f32_e32 v189, v74, v189
	v_add_f32_e32 v189, v75, v189
	v_mfma_f32_32x32x16_bf16 v[80:95], v[246:249], v[112:115], v[80:95]
	ds_read_b128 v[246:249], v169 offset:49152
	v_exp_f32_e32 v110, v110
	v_exp_f32_e32 v111, v111
	v_add_f32_e32 v189, v76, v189
	v_add_f32_e32 v189, v77, v189
	v_add_f32_e32 v189, v78, v189
	v_add_f32_e32 v189, v79, v189
	v_add_f32_e32 v160, v160, v189
	s_add_i32 m0, s26, 0x8000
	s_nop 0
	global_load_lds_dwordx4 v[140:141], off
	v_lshl_add_u64 v[140:141], v[140:141], 0, s[62:63]
	s_mov_b32 m0, s26
	s_nop 0
	global_load_lds_dwordx4 v[142:143], off
	v_lshl_add_u64 v[142:143], v[142:143], 0, s[62:63]
	s_waitcnt lgkmcnt(3)
	v_mfma_f32_32x32x16_bf16 v[218:233], v[234:237], v[124:127], v[0:15]
	ds_read_b64_tr_b16 v[190:191], v172 offset:8192
	ds_read_b64_tr_b16 v[192:193], v172 offset:8448
	v_add_f32_e32 v189, v96, v97
	v_add_f32_e32 v189, v98, v189
	v_add_f32_e32 v189, v99, v189
	v_add_f32_e32 v189, v100, v189
	v_exp_f32_e32 v80, v80
	s_waitcnt lgkmcnt(4)
; #define LAS __attribute__((address_space(3)))
; __device__ __forceinline__ void qkt(f32x16& p0, f32x16& p1, const char* Ks, const bf16x8* qr, const f32x16& negm, int r32, int hi) {
; #pragma unroll
;     for (int d0 = 0; d0 < 4; ++d0) { const int cb = (d0 * 16 + hi * 8) * 2;
;         const bf16x8 b0 = *reinterpret_cast<const bf16x8*>(Ks + KSWZ(r32, cb));
;         const bf16x8 b1 = *reinterpret_cast<const bf16x8*>(Ks + KSWZ(r32, 128 + cb));
;         if (d0 == 0) { p0 = __builtin_amdgcn_mfma_f32_32x32x16_bf16(b0, qr[0], negm, 0, 0, 0); p1 = __builtin_amdgcn_mfma_f32_32x32x16_bf16(b1, qr[0], negm, 0, 0, 0); }
;         else { p0 = __builtin_amdgcn_mfma_f32_32x32x16_bf16(b0, qr[d0], p0, 0, 0, 0); p1 = __builtin_amdgcn_mfma_f32_32x32x16_bf16(b1, qr[d0], p1, 0, 0, 0); } }
; }
; __device__ __forceinline__ int v_st(int k, int c) { const int kk = (k & ~0xC) | ((k & 4) << 1) | ((k & 8) >> 1); return ((kk >> 3) * 2 + (c >> 5)) * 512 + ((kk & 7) * 32 + (c & 31)) * 2; }
; __device__ __forceinline__ int v_rd_base(int lane) { return (((lane & 3) << 3) | (((lane >> 2) & 3) << 6) | (((lane >> 4) & 1) << 5)) + ((lane >> 5) & 1) * 1024; }
; template <int OFF> __device__ __forceinline__ s16x4 tr_read(int vb) {
;     return __builtin_bit_cast(s16x4, __builtin_amdgcn_ds_read_tr16_b64_v4i16((LAS v4i16_t*)(unsigned)(vb + OFF)));
; }
; template <int D0> __device__ __forceinline__ void pv_one(f32x16& od, int vb, bf16x8 pa0, bf16x8 pa1, bf16x8 pa2, bf16x8 pa3) {
;     const s16x4 l0 = tr_read<v_rd_off(D0, 0, 0)>(vb), h0 = tr_read<v_rd_off(D0, 0, 1)>(vb), l1 = tr_read<v_rd_off(D0, 1, 0)>(vb), h1 = tr_read<v_rd_off(D0, 1, 1)>(vb);
;     const s16x4 l2 = tr_read<v_rd_off(D0, 2, 0)>(vb), h2 = tr_read<v_rd_off(D0, 2, 1)>(vb), l3 = tr_read<v_rd_off(D0, 3, 0)>(vb), h3 = tr_read<v_rd_off(D0, 3, 1)>(vb);
;     ...
;     od = __builtin_amdgcn_mfma_f32_32x32x16_bf16(pa0, PK(l0, h0), od, 0, 0, 0);
;     od = __builtin_amdgcn_mfma_f32_32x32x16_bf16(pa1, PK(l1, h1), od, 0, 0, 0);
;     od = __builtin_amdgcn_mfma_f32_32x32x16_bf16(pa2, PK(l2, h2), od, 0, 0, 0);
;     od = __builtin_amdgcn_mfma_f32_32x32x16_bf16(pa3, PK(l3, h3), od, 0, 0, 0);
;     ...
; }
	v_mfma_f32_32x32x16_bf16 v[218:233], v[238:241], v[120:123], v[218:233]
	ds_read_b64_tr_b16 v[194:195], v172 offset:10240
	ds_read_b64_tr_b16 v[196:197], v172 offset:10496
	v_exp_f32_e32 v81, v81
	v_cvt_pk_bf16_f32 v48, v96, v97
	v_exp_f32_e32 v82, v82
	v_exp_f32_e32 v83, v83
	s_waitcnt lgkmcnt(5)
	v_mfma_f32_32x32x16_bf16 v[218:233], v[242:245], v[116:119], v[218:233]
	ds_read_b64_tr_b16 v[144:145], v172 offset:12288
	ds_read_b64_tr_b16 v[146:147], v172 offset:12544
	v_cvt_pk_bf16_f32 v49, v98, v99
	v_exp_f32_e32 v84, v84
	v_exp_f32_e32 v85, v85
	v_cvt_pk_bf16_f32 v50, v100, v101
	s_waitcnt lgkmcnt(6)
	v_mfma_f32_32x32x16_bf16 v[218:233], v[246:249], v[112:115], v[218:233]
	ds_read_b64_tr_b16 v[250:251], v172 offset:14336
	ds_read_b64_tr_b16 v[252:253], v172 offset:14592
	v_exp_f32_e32 v86, v86
	v_exp_f32_e32 v87, v87
	v_cvt_pk_bf16_f32 v51, v102, v103
	v_cvt_pk_bf16_f32 v52, v104, v105
	s_waitcnt lgkmcnt(6)
	v_mfma_f32_32x32x16_bf16 v[32:47], v[48:51], v[190:193], v[32:47]
	ds_read_b64_tr_b16 v[190:191], v172 offset:8704
	ds_read_b64_tr_b16 v[192:193], v172 offset:8960
	ds_read_b128 v[234:237], v164 offset:49152
	v_cvt_pk_bf16_f32 v53, v106, v107
	v_cvt_pk_bf16_f32 v54, v108, v109
	v_cvt_pk_bf16_f32 v55, v110, v111
	v_cvt_pk_bf16_f32 v56, v80, v81
	v_cvt_pk_bf16_f32 v57, v82, v83
	v_exp_f32_e32 v88, v88
	s_waitcnt lgkmcnt(7)
	v_mfma_f32_32x32x16_bf16 v[32:47], v[52:55], v[194:197], v[32:47]
	ds_read_b64_tr_b16 v[194:195], v172 offset:10752
	ds_read_b64_tr_b16 v[196:197], v172 offset:11008
	ds_read_b128 v[238:241], v166 offset:49152
	v_cvt_pk_bf16_f32 v58, v84, v85
	v_cvt_pk_bf16_f32 v59, v86, v87
	v_exp_f32_e32 v89, v89
	v_exp_f32_e32 v90, v90
	s_waitcnt lgkmcnt(4)
	v_mfma_f32_32x32x16_bf16 v[16:31], v[48:51], v[190:193], v[16:31]
	ds_read_b64_tr_b16 v[190:191], v172 offset:12800
	ds_read_b64_tr_b16 v[192:193], v172 offset:13056
	ds_read_b128 v[242:245], v168 offset:49152
	v_exp_f32_e32 v91, v91
	v_exp_f32_e32 v92, v92
	v_exp_f32_e32 v93, v93
	v_add_f32_e32 v189, v101, v189
	s_waitcnt lgkmcnt(4)
	v_mfma_f32_32x32x16_bf16 v[16:31], v[52:55], v[194:197], v[16:31]
	ds_read_b64_tr_b16 v[194:195], v172 offset:14848
	ds_read_b64_tr_b16 v[196:197], v172 offset:15104
	ds_read_b128 v[246:249], v170 offset:49152
	v_exp_f32_e32 v94, v94
	v_exp_f32_e32 v95, v95
	v_add_f32_e32 v189, v102, v189
	v_add_f32_e32 v189, v103, v189
	v_cvt_pk_bf16_f32 v60, v88, v89
	v_mfma_f32_32x32x16_bf16 v[32:47], v[56:59], v[144:147], v[32:47]
	v_cvt_pk_bf16_f32 v61, v90, v91
	v_cvt_pk_bf16_f32 v62, v92, v93
	v_cvt_pk_bf16_f32 v63, v94, v95
	v_add_f32_e32 v189, v104, v189
	v_add_f32_e32 v189, v105, v189
	v_add_f32_e32 v189, v106, v189
	v_add_f32_e32 v189, v107, v189
	v_mfma_f32_32x32x16_bf16 v[32:47], v[60:63], v[250:253], v[32:47]
	v_exp_f32_e32 v183, v218
	v_exp_f32_e32 v188, v219
	v_add_f32_e32 v189, v108, v189
	v_add_f32_e32 v189, v109, v189
	v_add_f32_e32 v189, v110, v189
	s_waitcnt lgkmcnt(4)
	v_mfma_f32_32x32x16_bf16 v[16:31], v[56:59], v[190:193], v[16:31]
	v_exp_f32_e32 v185, v220
	v_exp_f32_e32 v187, v221
	v_add_f32_e32 v189, v111, v189
	v_add_f32_e32 v189, v80, v189
	v_add_f32_e32 v189, v81, v189
	s_waitcnt lgkmcnt(1)
	v_mfma_f32_32x32x16_bf16 v[16:31], v[60:63], v[194:197], v[16:31]
	v_exp_f32_e32 v184, v222
	v_exp_f32_e32 v186, v223
	v_add_f32_e32 v189, v82, v189
	v_add_f32_e32 v189, v83, v189
	v_add_f32_e32 v189, v84, v189
	s_waitcnt vmcnt(2) lgkmcnt(0)
	s_barrier
	v_mfma_f32_32x32x16_bf16 v[64:79], v[234:237], v[124:127], v[0:15]
	ds_read_b128 v[234:237], v163 offset:57344
	v_exp_f32_e32 v181, v224
	v_exp_f32_e32 v182, v225
	v_add_f32_e32 v189, v85, v189
	v_add_f32_e32 v189, v86, v189
	v_add_f32_e32 v189, v87, v189
	v_mfma_f32_32x32x16_bf16 v[64:79], v[238:241], v[120:123], v[64:79]
	ds_read_b128 v[238:241], v165 offset:57344
	v_exp_f32_e32 v178, v226
	v_exp_f32_e32 v180, v227
	v_exp_f32_e32 v176, v228
	v_add_f32_e32 v189, v88, v189
	v_add_f32_e32 v189, v89, v189
	v_mfma_f32_32x32x16_bf16 v[64:79], v[242:245], v[116:119], v[64:79]
	ds_read_b128 v[242:245], v167 offset:57344
	v_exp_f32_e32 v179, v229
	v_exp_f32_e32 v175, v230
	v_exp_f32_e32 v177, v231
	v_add_f32_e32 v189, v90, v189
	v_add_f32_e32 v189, v91, v189
	v_mfma_f32_32x32x16_bf16 v[64:79], v[246:249], v[112:115], v[64:79]
	ds_read_b128 v[246:249], v169 offset:57344
	v_exp_f32_e32 v173, v232
	v_exp_f32_e32 v174, v233
	v_add_f32_e32 v189, v92, v189
	v_add_f32_e32 v189, v93, v189
	v_add_f32_e32 v189, v94, v189
	v_add_f32_e32 v189, v95, v189
	v_add_f32_e32 v160, v160, v189
	s_add_i32 m0, s26, 0xa000
	s_nop 0
	global_load_lds_dwordx4 v[140:141], off
	v_lshl_add_u64 v[140:141], v[140:141], 0, s[62:63]
	s_add_i32 m0, s26, 0x2000
	s_nop 0
	global_load_lds_dwordx4 v[142:143], off
	v_lshl_add_u64 v[142:143], v[142:143], 0, s[62:63]
	s_waitcnt lgkmcnt(3)
	v_mfma_f32_32x32x16_bf16 v[96:111], v[234:237], v[124:127], v[0:15]
	ds_read_b64_tr_b16 v[190:191], v172 offset:16384
	ds_read_b64_tr_b16 v[192:193], v172 offset:16640
	v_add_f32_e32 v189, v183, v188
	v_add_f32_e32 v189, v185, v189
	v_add_f32_e32 v189, v187, v189
	v_add_f32_e32 v189, v184, v189
	v_exp_f32_e32 v64, v64
	s_waitcnt lgkmcnt(4)
	v_mfma_f32_32x32x16_bf16 v[96:111], v[238:241], v[120:123], v[96:111]
	ds_read_b64_tr_b16 v[194:195], v172 offset:18432
	ds_read_b64_tr_b16 v[196:197], v172 offset:18688
	v_exp_f32_e32 v65, v65
	v_cvt_pk_bf16_f32 v48, v183, v188
	v_exp_f32_e32 v66, v66
	v_exp_f32_e32 v67, v67
	s_waitcnt lgkmcnt(5)
	v_mfma_f32_32x32x16_bf16 v[96:111], v[242:245], v[116:119], v[96:111]
	ds_read_b64_tr_b16 v[144:145], v172 offset:20480
	ds_read_b64_tr_b16 v[146:147], v172 offset:20736
	v_cvt_pk_bf16_f32 v49, v185, v187
	v_exp_f32_e32 v68, v68
	v_exp_f32_e32 v69, v69
	v_cvt_pk_bf16_f32 v50, v184, v186
	s_waitcnt lgkmcnt(6)
; #define LAS __attribute__((address_space(3)))
; __device__ __forceinline__ void qkt(f32x16& p0, f32x16& p1, const char* Ks, const bf16x8* qr, const f32x16& negm, int r32, int hi) {
; #pragma unroll
;     for (int d0 = 0; d0 < 4; ++d0) { const int cb = (d0 * 16 + hi * 8) * 2;
;         const bf16x8 b0 = *reinterpret_cast<const bf16x8*>(Ks + KSWZ(r32, cb));
;         const bf16x8 b1 = *reinterpret_cast<const bf16x8*>(Ks + KSWZ(r32, 128 + cb));
;         if (d0 == 0) { p0 = __builtin_amdgcn_mfma_f32_32x32x16_bf16(b0, qr[0], negm, 0, 0, 0); p1 = __builtin_amdgcn_mfma_f32_32x32x16_bf16(b1, qr[0], negm, 0, 0, 0); }
;         else { p0 = __builtin_amdgcn_mfma_f32_32x32x16_bf16(b0, qr[d0], p0, 0, 0, 0); p1 = __builtin_amdgcn_mfma_f32_32x32x16_bf16(b1, qr[d0], p1, 0, 0, 0); } }
; }
; __device__ __forceinline__ int v_st(int k, int c) { const int kk = (k & ~0xC) | ((k & 4) << 1) | ((k & 8) >> 1); return ((kk >> 3) * 2 + (c >> 5)) * 512 + ((kk & 7) * 32 + (c & 31)) * 2; }
; __device__ __forceinline__ int v_rd_base(int lane) { return (((lane & 3) << 3) | (((lane >> 2) & 3) << 6) | (((lane >> 4) & 1) << 5)) + ((lane >> 5) & 1) * 1024; }
; template <int OFF> __device__ __forceinline__ s16x4 tr_read(int vb) {
;     return __builtin_bit_cast(s16x4, __builtin_amdgcn_ds_read_tr16_b64_v4i16((LAS v4i16_t*)(unsigned)(vb + OFF)));
; }
; template <int D0> __device__ __forceinline__ void pv_one(f32x16& od, int vb, bf16x8 pa0, bf16x8 pa1, bf16x8 pa2, bf16x8 pa3) {
;     const s16x4 l0 = tr_read<v_rd_off(D0, 0, 0)>(vb), h0 = tr_read<v_rd_off(D0, 0, 1)>(vb), l1 = tr_read<v_rd_off(D0, 1, 0)>(vb), h1 = tr_read<v_rd_off(D0, 1, 1)>(vb);
;     const s16x4 l2 = tr_read<v_rd_off(D0, 2, 0)>(vb), h2 = tr_read<v_rd_off(D0, 2, 1)>(vb), l3 = tr_read<v_rd_off(D0, 3, 0)>(vb), h3 = tr_read<v_rd_off(D0, 3, 1)>(vb);
;     ...
;     od = __builtin_amdgcn_mfma_f32_32x32x16_bf16(pa0, PK(l0, h0), od, 0, 0, 0);
;     od = __builtin_amdgcn_mfma_f32_32x32x16_bf16(pa1, PK(l1, h1), od, 0, 0, 0);
;     od = __builtin_amdgcn_mfma_f32_32x32x16_bf16(pa2, PK(l2, h2), od, 0, 0, 0);
;     od = __builtin_amdgcn_mfma_f32_32x32x16_bf16(pa3, PK(l3, h3), od, 0, 0, 0);
;     ...
; }
	v_mfma_f32_32x32x16_bf16 v[96:111], v[246:249], v[112:115], v[96:111]
	ds_read_b64_tr_b16 v[250:251], v172 offset:22528
	ds_read_b64_tr_b16 v[252:253], v172 offset:22784
	v_exp_f32_e32 v70, v70
	v_exp_f32_e32 v71, v71
	v_cvt_pk_bf16_f32 v51, v181, v182
	v_cvt_pk_bf16_f32 v52, v178, v180
	s_waitcnt lgkmcnt(6)
	v_mfma_f32_32x32x16_bf16 v[32:47], v[48:51], v[190:193], v[32:47]
	ds_read_b64_tr_b16 v[190:191], v172 offset:16896
	ds_read_b64_tr_b16 v[192:193], v172 offset:17152
	ds_read_b128 v[234:237], v164 offset:57344
	v_cvt_pk_bf16_f32 v53, v176, v179
	v_cvt_pk_bf16_f32 v54, v175, v177
	v_cvt_pk_bf16_f32 v55, v173, v174
	v_cvt_pk_bf16_f32 v56, v64, v65
	v_cvt_pk_bf16_f32 v57, v66, v67
	v_exp_f32_e32 v72, v72
	s_waitcnt lgkmcnt(7)
	v_mfma_f32_32x32x16_bf16 v[32:47], v[52:55], v[194:197], v[32:47]
	ds_read_b64_tr_b16 v[194:195], v172 offset:18944
	ds_read_b64_tr_b16 v[196:197], v172 offset:19200
	ds_read_b128 v[238:241], v166 offset:57344
	v_cvt_pk_bf16_f32 v58, v68, v69
	v_cvt_pk_bf16_f32 v59, v70, v71
	v_exp_f32_e32 v73, v73
	v_exp_f32_e32 v74, v74
	s_waitcnt lgkmcnt(4)
	v_mfma_f32_32x32x16_bf16 v[16:31], v[48:51], v[190:193], v[16:31]
	ds_read_b64_tr_b16 v[190:191], v172 offset:20992
	ds_read_b64_tr_b16 v[192:193], v172 offset:21248
	ds_read_b128 v[242:245], v168 offset:57344
	v_exp_f32_e32 v75, v75
	v_exp_f32_e32 v76, v76
	v_exp_f32_e32 v77, v77
	v_add_f32_e32 v189, v186, v189
	s_waitcnt lgkmcnt(4)
	v_mfma_f32_32x32x16_bf16 v[16:31], v[52:55], v[194:197], v[16:31]
	ds_read_b64_tr_b16 v[194:195], v172 offset:23040
	ds_read_b64_tr_b16 v[196:197], v172 offset:23296
	ds_read_b128 v[246:249], v170 offset:57344
	v_exp_f32_e32 v78, v78
	v_exp_f32_e32 v79, v79
	v_add_f32_e32 v189, v181, v189
	v_add_f32_e32 v189, v182, v189
	v_cvt_pk_bf16_f32 v60, v72, v73
	v_mfma_f32_32x32x16_bf16 v[32:47], v[56:59], v[144:147], v[32:47]
	v_cvt_pk_bf16_f32 v61, v74, v75
	v_cvt_pk_bf16_f32 v62, v76, v77
	v_cvt_pk_bf16_f32 v63, v78, v79
	v_add_f32_e32 v189, v178, v189
	v_add_f32_e32 v189, v180, v189
	v_add_f32_e32 v189, v176, v189
	v_add_f32_e32 v189, v179, v189
	v_mfma_f32_32x32x16_bf16 v[32:47], v[60:63], v[250:253], v[32:47]
	v_exp_f32_e32 v96, v96
	v_exp_f32_e32 v97, v97
	v_add_f32_e32 v189, v175, v189
	v_add_f32_e32 v189, v177, v189
	v_add_f32_e32 v189, v173, v189
	s_waitcnt lgkmcnt(4)
	v_mfma_f32_32x32x16_bf16 v[16:31], v[56:59], v[190:193], v[16:31]
	v_exp_f32_e32 v98, v98
	v_exp_f32_e32 v99, v99
	v_add_f32_e32 v189, v174, v189
	v_add_f32_e32 v189, v64, v189
	v_add_f32_e32 v189, v65, v189
	s_waitcnt lgkmcnt(1)
	v_mfma_f32_32x32x16_bf16 v[16:31], v[60:63], v[194:197], v[16:31]
	v_exp_f32_e32 v100, v100
	v_exp_f32_e32 v101, v101
	v_add_f32_e32 v189, v66, v189
	v_add_f32_e32 v189, v67, v189
	v_add_f32_e32 v189, v68, v189
	s_waitcnt vmcnt(2) lgkmcnt(0)
	s_barrier
	v_mfma_f32_32x32x16_bf16 v[80:95], v[234:237], v[124:127], v[0:15]
	ds_read_b128 v[234:237], v163 offset:32768
	v_exp_f32_e32 v102, v102
	v_exp_f32_e32 v103, v103
	v_add_f32_e32 v189, v69, v189
	v_add_f32_e32 v189, v70, v189
	v_add_f32_e32 v189, v71, v189
	v_mfma_f32_32x32x16_bf16 v[80:95], v[238:241], v[120:123], v[80:95]
	ds_read_b128 v[238:241], v165 offset:32768
	v_exp_f32_e32 v104, v104
	v_exp_f32_e32 v105, v105
	v_exp_f32_e32 v106, v106
	v_add_f32_e32 v189, v72, v189
	v_add_f32_e32 v189, v73, v189
	v_mfma_f32_32x32x16_bf16 v[80:95], v[242:245], v[116:119], v[80:95]
	ds_read_b128 v[242:245], v167 offset:32768
	v_exp_f32_e32 v107, v107
	v_exp_f32_e32 v108, v108
	v_exp_f32_e32 v109, v109
	v_add_f32_e32 v189, v74, v189
	v_add_f32_e32 v189, v75, v189
	v_mfma_f32_32x32x16_bf16 v[80:95], v[246:249], v[112:115], v[80:95]
	ds_read_b128 v[246:249], v169 offset:32768
	v_exp_f32_e32 v110, v110
	v_exp_f32_e32 v111, v111
	v_add_f32_e32 v189, v76, v189
	v_add_f32_e32 v189, v77, v189
	v_add_f32_e32 v189, v78, v189
	v_add_f32_e32 v189, v79, v189
	v_add_f32_e32 v160, v160, v189
	s_add_i32 m0, s26, 0xc000
	s_nop 0
	global_load_lds_dwordx4 v[140:141], off
	v_lshl_add_u64 v[140:141], v[140:141], 0, s[62:63]
	s_add_i32 m0, s26, 0x4000
	s_nop 0
	global_load_lds_dwordx4 v[142:143], off
	v_lshl_add_u64 v[142:143], v[142:143], 0, s[62:63]
	s_waitcnt lgkmcnt(3)
	v_mfma_f32_32x32x16_bf16 v[218:233], v[234:237], v[124:127], v[0:15]
	ds_read_b64_tr_b16 v[190:191], v172 offset:24576
	ds_read_b64_tr_b16 v[192:193], v172 offset:24832
	v_add_f32_e32 v189, v96, v97
	v_add_f32_e32 v189, v98, v189
	v_add_f32_e32 v189, v99, v189
	v_add_f32_e32 v189, v100, v189
	v_exp_f32_e32 v80, v80
	s_waitcnt lgkmcnt(4)
	v_mfma_f32_32x32x16_bf16 v[218:233], v[238:241], v[120:123], v[218:233]
	ds_read_b64_tr_b16 v[194:195], v172 offset:26624
	ds_read_b64_tr_b16 v[196:197], v172 offset:26880
	v_exp_f32_e32 v81, v81
	v_cvt_pk_bf16_f32 v48, v96, v97
	v_exp_f32_e32 v82, v82
	v_exp_f32_e32 v83, v83
	s_waitcnt lgkmcnt(5)
	v_mfma_f32_32x32x16_bf16 v[218:233], v[242:245], v[116:119], v[218:233]
	ds_read_b64_tr_b16 v[144:145], v172 offset:28672
	ds_read_b64_tr_b16 v[146:147], v172 offset:28928
	v_cvt_pk_bf16_f32 v49, v98, v99
	v_exp_f32_e32 v84, v84
	v_exp_f32_e32 v85, v85
	v_cvt_pk_bf16_f32 v50, v100, v101
	s_waitcnt lgkmcnt(6)
	v_mfma_f32_32x32x16_bf16 v[218:233], v[246:249], v[112:115], v[218:233]
	ds_read_b64_tr_b16 v[250:251], v172 offset:30720
	ds_read_b64_tr_b16 v[252:253], v172 offset:30976
	v_exp_f32_e32 v86, v86
	v_exp_f32_e32 v87, v87
	v_cvt_pk_bf16_f32 v51, v102, v103
	v_cvt_pk_bf16_f32 v52, v104, v105
	s_waitcnt lgkmcnt(6)
	v_mfma_f32_32x32x16_bf16 v[32:47], v[48:51], v[190:193], v[32:47]
	ds_read_b64_tr_b16 v[190:191], v172 offset:25088
	ds_read_b64_tr_b16 v[192:193], v172 offset:25344
	ds_read_b128 v[234:237], v164 offset:32768
	v_cvt_pk_bf16_f32 v53, v106, v107
	v_cvt_pk_bf16_f32 v54, v108, v109
	v_cvt_pk_bf16_f32 v55, v110, v111
	v_cvt_pk_bf16_f32 v56, v80, v81
	v_cvt_pk_bf16_f32 v57, v82, v83
	v_exp_f32_e32 v88, v88
	s_waitcnt lgkmcnt(7)
; #define SBAR() __builtin_amdgcn_sched_barrier(0)
; #define DMA(t) do { const int t_ = (t) < NT ? (t) : NT - 1; const long off_ = (long)t_ * (KVBLK * LDK); \
;         __builtin_amdgcn_global_load_lds((const unsigned*)(kptr + off_), (LAS unsigned*)(ldsK + SLOT(t)), 16, 0, 0); \
;         __builtin_amdgcn_global_load_lds((const unsigned*)(vptr + off_), (LAS unsigned*)(ldsV + SLOT(t)), 16, 0, 0); } while (0)
; #define HALF(PX0, PX1, PY0, PY1, j_, MORE) do { \
;         SBAR(); if (MORE) DMA((j_) + 2); qkt(PX0, PX1, K_lds + SLOT(j_), qr, negm, r32, hi); \
;         finishSM(PY0, PY1, l_reg, pa0, pa1, pa2, pa3); \
;         pv_d0(o, vb0 + SLOT((j_) - 1), pa0, pa1, pa2, pa3); partialSM(PX0); \
;         if (MORE) WBAR(2); else WBAR(0); } while (0)
; __device__ __forceinline__ void attn_body(const bf16* __restrict__ Qb, const bf16* __restrict__ Kh, const bf16* __restrict__ Vh, bf16* __restrict__ Ob, int seq, float m0l2, char* lds, bool pre, bool post) {
;     ...
;     for (; j + 4 < NT; j += 2) {
;         HALF(pB0, pB1, pA0, pA1, j, true);
;         HALF(pA0, pA1, pB0, pB1, j + 1, true);
;     }
;     HALF(pB0, pB1, pA0, pA1, j, true);
;     HALF(pA0, pA1, pB0, pB1, j + 1, false);
;     if (post) { DMA(0); DMA(1); }
;     SBAR(); qkt(pB0, pB1, K_lds + SLOT(NT - 1), qr, negm, r32, hi);
;     finishSM(pA0, pA1, l_reg, pa0, pa1, pa2, pa3); SBAR();
;     pv_d0(o, vb0 + SLOT(NT - 2), pa0, pa1, pa2, pa3); partialSM(pB0);
	v_mfma_f32_32x32x16_bf16 v[32:47], v[52:55], v[194:197], v[32:47]
	ds_read_b64_tr_b16 v[194:195], v172 offset:27136
	ds_read_b64_tr_b16 v[196:197], v172 offset:27392
	ds_read_b128 v[238:241], v166 offset:32768
	v_cvt_pk_bf16_f32 v58, v84, v85
	v_cvt_pk_bf16_f32 v59, v86, v87
	v_exp_f32_e32 v89, v89
	v_exp_f32_e32 v90, v90
	s_waitcnt lgkmcnt(4)
	v_mfma_f32_32x32x16_bf16 v[16:31], v[48:51], v[190:193], v[16:31]
	ds_read_b64_tr_b16 v[190:191], v172 offset:29184
	ds_read_b64_tr_b16 v[192:193], v172 offset:29440
	ds_read_b128 v[242:245], v168 offset:32768
	v_exp_f32_e32 v91, v91
	v_exp_f32_e32 v92, v92
	v_exp_f32_e32 v93, v93
	v_add_f32_e32 v189, v101, v189
	s_waitcnt lgkmcnt(4)
	v_mfma_f32_32x32x16_bf16 v[16:31], v[52:55], v[194:197], v[16:31]
	ds_read_b64_tr_b16 v[194:195], v172 offset:31232
	ds_read_b64_tr_b16 v[196:197], v172 offset:31488
	ds_read_b128 v[246:249], v170 offset:32768
	v_exp_f32_e32 v94, v94
	v_exp_f32_e32 v95, v95
	v_add_f32_e32 v189, v102, v189
	v_add_f32_e32 v189, v103, v189
	v_cvt_pk_bf16_f32 v60, v88, v89
	v_mfma_f32_32x32x16_bf16 v[32:47], v[56:59], v[144:147], v[32:47]
	v_cvt_pk_bf16_f32 v61, v90, v91
	v_cvt_pk_bf16_f32 v62, v92, v93
	v_cvt_pk_bf16_f32 v63, v94, v95
	v_add_f32_e32 v189, v104, v189
	v_add_f32_e32 v189, v105, v189
	v_add_f32_e32 v189, v106, v189
	v_add_f32_e32 v189, v107, v189
	v_mfma_f32_32x32x16_bf16 v[32:47], v[60:63], v[250:253], v[32:47]
	v_exp_f32_e32 v183, v218
	v_exp_f32_e32 v188, v219
	v_add_f32_e32 v189, v108, v189
	v_add_f32_e32 v189, v109, v189
	v_add_f32_e32 v189, v110, v189
	s_waitcnt lgkmcnt(4)
	v_mfma_f32_32x32x16_bf16 v[16:31], v[56:59], v[190:193], v[16:31]
	v_exp_f32_e32 v185, v220
	v_exp_f32_e32 v187, v221
	v_add_f32_e32 v189, v111, v189
	v_add_f32_e32 v189, v80, v189
	v_add_f32_e32 v189, v81, v189
	s_waitcnt lgkmcnt(1)
	v_mfma_f32_32x32x16_bf16 v[16:31], v[60:63], v[194:197], v[16:31]
	v_exp_f32_e32 v184, v222
	v_exp_f32_e32 v186, v223
	v_add_f32_e32 v189, v82, v189
	v_add_f32_e32 v189, v83, v189
	v_add_f32_e32 v189, v84, v189
	s_waitcnt vmcnt(2) lgkmcnt(0)
	s_barrier
	v_mfma_f32_32x32x16_bf16 v[64:79], v[234:237], v[124:127], v[0:15]
	ds_read_b128 v[234:237], v163 offset:40960
	v_exp_f32_e32 v181, v224
	v_exp_f32_e32 v182, v225
	v_add_f32_e32 v189, v85, v189
	v_add_f32_e32 v189, v86, v189
	v_add_f32_e32 v189, v87, v189
	v_mfma_f32_32x32x16_bf16 v[64:79], v[238:241], v[120:123], v[64:79]
	ds_read_b128 v[238:241], v165 offset:40960
	v_exp_f32_e32 v178, v226
	v_exp_f32_e32 v180, v227
	v_exp_f32_e32 v176, v228
	v_add_f32_e32 v189, v88, v189
	v_add_f32_e32 v189, v89, v189
	v_mfma_f32_32x32x16_bf16 v[64:79], v[242:245], v[116:119], v[64:79]
	ds_read_b128 v[242:245], v167 offset:40960
	v_exp_f32_e32 v179, v229
	v_exp_f32_e32 v175, v230
	v_exp_f32_e32 v177, v231
	v_add_f32_e32 v189, v90, v189
	v_add_f32_e32 v189, v91, v189
	v_mfma_f32_32x32x16_bf16 v[64:79], v[246:249], v[112:115], v[64:79]
	ds_read_b128 v[246:249], v169 offset:40960
	v_exp_f32_e32 v173, v232
	v_exp_f32_e32 v174, v233
	v_add_f32_e32 v189, v92, v189
	v_add_f32_e32 v189, v93, v189
	v_add_f32_e32 v189, v94, v189
	v_add_f32_e32 v189, v95, v189
	v_add_f32_e32 v160, v160, v189
	s_add_i32 s7, s7, 4
	s_cmp_lt_u32 s7, 62
	s_cbranch_scc1 .LBB0_27
	s_setprio 0
	s_waitcnt lgkmcnt(0)
	v_mov_b64_e32 v[48:49], v[0:1]
	v_mov_b64_e32 v[50:51], v[2:3]
	v_mov_b64_e32 v[52:53], v[4:5]
	v_mov_b64_e32 v[54:55], v[6:7]
	v_mov_b64_e32 v[56:57], v[8:9]
	v_mov_b64_e32 v[58:59], v[10:11]
	v_mov_b64_e32 v[60:61], v[12:13]
	v_mov_b64_e32 v[62:63], v[14:15]
	s_nop 7
	s_add_i32 s6, s6, s24
	s_cmpk_lt_i32 s6, 0x400
	s_cselect_b64 s[6:7], -1, 0
	s_or_b64 s[6:7], s[6:7], s[8:9]
	s_and_b64 s[6:7], s[86:87], s[6:7]
	s_mov_b64 s[38:39], 0x10c000
	v_lshl_add_u64 v[80:81], v[132:133], 0, s[38:39]
	s_add_i32 m0, s26, 0xe000
	v_add_u32_e32 v172, 0, v129
	global_load_lds_dwordx4 v[80:81], off
	v_lshl_add_u64 v[80:81], v[134:135], 0, s[38:39]
	s_add_i32 m0, s26, 0x6000
	s_cmp_lg_u32 0, -1
	global_load_lds_dwordx4 v[80:81], off
	ds_read_b128 v[96:99], v154 offset:40960
	ds_read_b128 v[140:143], v162 offset:40960
	s_waitcnt lgkmcnt(0)
	v_mfma_f32_32x32x16_bf16 v[80:95], v[96:99], v[124:127], v[48:63]
	s_cselect_b32 s27, 0, 0
	v_add_u32_e32 v221, s27, v129
	v_exp_f32_e32 v144, v68
	v_exp_f32_e32 v145, v69
	v_exp_f32_e32 v146, v70
	v_exp_f32_e32 v147, v71
	v_exp_f32_e32 v163, v72
	v_mfma_f32_32x32x16_bf16 v[96:111], v[140:143], v[124:127], v[48:63]
	ds_read_b128 v[140:143], v153 offset:40960
	v_exp_f32_e32 v168, v77
	v_exp_f32_e32 v169, v78
	v_exp_f32_e32 v170, v79
	s_waitcnt lgkmcnt(0)
	v_mfma_f32_32x32x16_bf16 v[80:95], v[140:143], v[120:123], v[80:95]
	ds_read_b128 v[140:143], v157 offset:40960
	s_waitcnt lgkmcnt(0)
	v_mfma_f32_32x32x16_bf16 v[96:111], v[140:143], v[120:123], v[96:111]
	ds_read_b128 v[140:143], v156 offset:40960
	s_waitcnt lgkmcnt(0)
	v_mfma_f32_32x32x16_bf16 v[80:95], v[140:143], v[116:119], v[80:95]
	ds_read_b128 v[140:143], v158 offset:40960
	ds_read_b128 v[164:167], v155 offset:40960
	ds_read_b128 v[190:193], v159 offset:40960
	s_waitcnt lgkmcnt(0)
	v_mfma_f32_32x32x16_bf16 v[96:111], v[140:143], v[116:119], v[96:111]
	v_exp_f32_e32 v140, v64
	v_exp_f32_e32 v141, v65
	v_exp_f32_e32 v142, v66
	v_exp_f32_e32 v143, v67
	v_cvt_pk_bf16_f32 v64, v183, v188
	v_cvt_pk_bf16_f32 v65, v185, v187
	v_cvt_pk_bf16_f32 v66, v184, v186
	v_mfma_f32_32x32x16_bf16 v[80:95], v[164:167], v[112:115], v[80:95]
	v_exp_f32_e32 v164, v73
	v_exp_f32_e32 v165, v74
	v_exp_f32_e32 v166, v75
	v_exp_f32_e32 v167, v76
	v_cvt_pk_bf16_f32 v67, v181, v182
	v_cvt_pk_bf16_f32 v68, v178, v180
	v_cvt_pk_bf16_f32 v69, v176, v179
	v_mfma_f32_32x32x16_bf16 v[96:111], v[190:193], v[112:115], v[96:111]
	v_cvt_pk_bf16_f32 v70, v175, v177
	v_cvt_pk_bf16_f32 v71, v173, v174
	v_cvt_pk_bf16_f32 v72, v140, v141
	v_cvt_pk_bf16_f32 v73, v142, v143
	v_cvt_pk_bf16_f32 v74, v144, v145
	v_cvt_pk_bf16_f32 v75, v146, v147
	v_cvt_pk_bf16_f32 v76, v163, v164
	v_cvt_pk_bf16_f32 v77, v165, v166
	v_cvt_pk_bf16_f32 v78, v167, v168
	v_cvt_pk_bf16_f32 v79, v169, v170
	ds_read_b64_tr_b16 v[190:191], v172
	ds_read_b64_tr_b16 v[192:193], v221 offset:256
	s_waitcnt lgkmcnt(0)
; #define SBAR() __builtin_amdgcn_sched_barrier(0)
; #define DMA(t) do { const int t_ = (t) < NT ? (t) : NT - 1; const long off_ = (long)t_ * (KVBLK * LDK); \
;         __builtin_amdgcn_global_load_lds((const unsigned*)(kptr + off_), (LAS unsigned*)(ldsK + SLOT(t)), 16, 0, 0); \
;         __builtin_amdgcn_global_load_lds((const unsigned*)(vptr + off_), (LAS unsigned*)(ldsV + SLOT(t)), 16, 0, 0); } while (0)
; #define HALF(PX0, PX1, PY0, PY1, j_, MORE) do { \
;         SBAR(); if (MORE) DMA((j_) + 2); qkt(PX0, PX1, K_lds + SLOT(j_), qr, negm, r32, hi); \
;         finishSM(PY0, PY1, l_reg, pa0, pa1, pa2, pa3); \
;         pv_d0(o, vb0 + SLOT((j_) - 1), pa0, pa1, pa2, pa3); partialSM(PX0); \
;         if (MORE) WBAR(2); else WBAR(0); } while (0)
; __device__ __forceinline__ void attn_body(const bf16* __restrict__ Qb, const bf16* __restrict__ Kh, const bf16* __restrict__ Vh, bf16* __restrict__ Ob, int seq, float m0l2, char* lds, bool pre, bool post) {
;     ...
;     HALF(pB0, pB1, pA0, pA1, j, true);
;     HALF(pA0, pA1, pB0, pB1, j + 1, false);
;     if (post) { DMA(0); DMA(1); }
;     SBAR(); qkt(pB0, pB1, K_lds + SLOT(NT - 1), qr, negm, r32, hi);
	v_mfma_f32_32x32x16_bf16 v[32:47], v[64:67], v[190:193], v[32:47]
	ds_read_b64_tr_b16 v[190:191], v221 offset:2048
	ds_read_b64_tr_b16 v[192:193], v221 offset:2304
	s_nop 0
	v_exp_f32_e32 v172, v80
	v_exp_f32_e32 v189, v81
	v_exp_f32_e32 v198, v90
	v_exp_f32_e32 v199, v91
	v_exp_f32_e32 v217, v92
	v_exp_f32_e32 v218, v93
	s_waitcnt lgkmcnt(0)
	v_mfma_f32_32x32x16_bf16 v[32:47], v[68:71], v[190:193], v[32:47]
	ds_read_b64_tr_b16 v[190:191], v221 offset:4096
	ds_read_b64_tr_b16 v[192:193], v221 offset:4352
	v_exp_f32_e32 v219, v94
	v_exp_f32_e32 v220, v95
	s_waitcnt lgkmcnt(0)
	v_mfma_f32_32x32x16_bf16 v[32:47], v[72:75], v[190:193], v[32:47]
	ds_read_b64_tr_b16 v[190:191], v221 offset:6144
	ds_read_b64_tr_b16 v[192:193], v221 offset:6400
	s_waitcnt lgkmcnt(0)
	v_mfma_f32_32x32x16_bf16 v[32:47], v[76:79], v[190:193], v[32:47]
	ds_read_b64_tr_b16 v[190:191], v221 offset:512
	ds_read_b64_tr_b16 v[192:193], v221 offset:768
	ds_read_b64_tr_b16 v[194:195], v221 offset:2560
	s_waitcnt lgkmcnt(0)
	v_mfma_f32_32x32x16_bf16 v[16:31], v[64:67], v[190:193], v[16:31]
	ds_read_b64_tr_b16 v[196:197], v221 offset:2816
	ds_read_b64_tr_b16 v[64:65], v221 offset:4608
	ds_read_b64_tr_b16 v[66:67], v221 offset:4864
	ds_read_b64_tr_b16 v[222:223], v221 offset:6656
	ds_read_b64_tr_b16 v[224:225], v221 offset:6912
	v_exp_f32_e32 v190, v82
	v_exp_f32_e32 v191, v83
	v_exp_f32_e32 v192, v84
	v_exp_f32_e32 v193, v85
	s_waitcnt vmcnt(2) lgkmcnt(0)
	s_barrier
	s_waitcnt lgkmcnt(0)
	v_mfma_f32_32x32x16_bf16 v[16:31], v[68:71], v[194:197], v[16:31]
	v_exp_f32_e32 v194, v86
	v_exp_f32_e32 v195, v87
	v_exp_f32_e32 v196, v88
	v_exp_f32_e32 v197, v89
	v_mfma_f32_32x32x16_bf16 v[16:31], v[72:75], v[64:67], v[16:31]
	v_mfma_f32_32x32x16_bf16 v[16:31], v[76:79], v[222:225], v[16:31]
	ds_read_b128 v[64:67], v154 offset:49152
	ds_read_b128 v[222:225], v162 offset:49152
	v_exp_f32_e32 v96, v96
	v_exp_f32_e32 v97, v97
	v_exp_f32_e32 v98, v98
	v_exp_f32_e32 v99, v99
	v_exp_f32_e32 v100, v100
	v_exp_f32_e32 v101, v101
	v_exp_f32_e32 v102, v102
	s_waitcnt lgkmcnt(0)
	v_mfma_f32_32x32x16_bf16 v[80:95], v[64:67], v[124:127], v[48:63]
	v_exp_f32_e32 v103, v103
	v_exp_f32_e32 v104, v104
	v_exp_f32_e32 v105, v105
	v_exp_f32_e32 v106, v106
	v_exp_f32_e32 v107, v107
	v_exp_f32_e32 v108, v108
	v_exp_f32_e32 v109, v109
	v_mfma_f32_32x32x16_bf16 v[64:79], v[222:225], v[124:127], v[48:63]
	ds_read_b128 v[222:225], v153 offset:49152
	v_exp_f32_e32 v110, v110
	v_exp_f32_e32 v111, v111
	s_andn2_b64 vcc, exec, s[6:7]
	s_waitcnt lgkmcnt(0)
	v_mfma_f32_32x32x16_bf16 v[80:95], v[222:225], v[120:123], v[80:95]
	ds_read_b128 v[222:225], v157 offset:49152
	s_waitcnt lgkmcnt(0)
	v_mfma_f32_32x32x16_bf16 v[64:79], v[222:225], v[120:123], v[64:79]
	ds_read_b128 v[222:225], v156 offset:49152
	s_waitcnt lgkmcnt(0)
	v_mfma_f32_32x32x16_bf16 v[80:95], v[222:225], v[116:119], v[80:95]
	ds_read_b128 v[222:225], v158 offset:49152
	s_waitcnt lgkmcnt(0)
	v_mfma_f32_32x32x16_bf16 v[64:79], v[222:225], v[116:119], v[64:79]
	ds_read_b128 v[222:225], v155 offset:49152
	s_waitcnt lgkmcnt(0)
	v_mfma_f32_32x32x16_bf16 v[80:95], v[222:225], v[112:115], v[80:95]
	ds_read_b128 v[222:225], v159 offset:49152
	s_waitcnt lgkmcnt(0)
	v_mfma_f32_32x32x16_bf16 v[64:79], v[222:225], v[112:115], v[64:79]
	v_cvt_pk_bf16_f32 v222, v172, v189
	v_cvt_pk_bf16_f32 v223, v190, v191
	v_cvt_pk_bf16_f32 v224, v192, v193
	v_cvt_pk_bf16_f32 v225, v194, v195
	v_cvt_pk_bf16_f32 v226, v196, v197
	v_cvt_pk_bf16_f32 v227, v198, v199
	v_cvt_pk_bf16_f32 v228, v217, v218
	v_cvt_pk_bf16_f32 v229, v219, v220
	v_cvt_pk_bf16_f32 v230, v96, v97
	v_cvt_pk_bf16_f32 v231, v98, v99
	v_cvt_pk_bf16_f32 v232, v100, v101
	v_cvt_pk_bf16_f32 v233, v102, v103
	v_cvt_pk_bf16_f32 v234, v104, v105
	v_cvt_pk_bf16_f32 v235, v106, v107
	v_cvt_pk_bf16_f32 v236, v108, v109
	v_cvt_pk_bf16_f32 v237, v110, v111
	ds_read_b64_tr_b16 v[238:239], v221 offset:8192
	ds_read_b64_tr_b16 v[240:241], v221 offset:8448
	s_waitcnt lgkmcnt(0)
	v_mfma_f32_32x32x16_bf16 v[32:47], v[222:225], v[238:241], v[32:47]
	ds_read_b64_tr_b16 v[238:239], v221 offset:10240
	ds_read_b64_tr_b16 v[240:241], v221 offset:10496
	s_waitcnt lgkmcnt(0)
	v_mfma_f32_32x32x16_bf16 v[32:47], v[226:229], v[238:241], v[32:47]
	ds_read_b64_tr_b16 v[238:239], v221 offset:12288
	ds_read_b64_tr_b16 v[240:241], v221 offset:12544
	s_waitcnt lgkmcnt(0)
	v_mfma_f32_32x32x16_bf16 v[32:47], v[230:233], v[238:241], v[32:47]
	ds_read_b64_tr_b16 v[238:239], v221 offset:14336
	ds_read_b64_tr_b16 v[240:241], v221 offset:14592
	s_waitcnt lgkmcnt(0)
	v_mfma_f32_32x32x16_bf16 v[32:47], v[234:237], v[238:241], v[32:47]
	ds_read_b64_tr_b16 v[238:239], v221 offset:8704
	ds_read_b64_tr_b16 v[240:241], v221 offset:8960
	s_waitcnt lgkmcnt(0)
	v_mfma_f32_32x32x16_bf16 v[16:31], v[222:225], v[238:241], v[16:31]
	ds_read_b64_tr_b16 v[222:223], v221 offset:10752
	ds_read_b64_tr_b16 v[224:225], v221 offset:11008
	s_waitcnt lgkmcnt(0)
	v_mfma_f32_32x32x16_bf16 v[16:31], v[226:229], v[222:225], v[16:31]
	ds_read_b64_tr_b16 v[222:223], v221 offset:12800
	ds_read_b64_tr_b16 v[224:225], v221 offset:13056
	s_waitcnt lgkmcnt(0)
	v_mfma_f32_32x32x16_bf16 v[16:31], v[230:233], v[222:225], v[16:31]
	ds_read_b64_tr_b16 v[222:223], v221 offset:14848
	ds_read_b64_tr_b16 v[224:225], v221 offset:15104
	s_waitcnt vmcnt(0) lgkmcnt(0)
	s_barrier
	s_waitcnt lgkmcnt(0)
	v_mfma_f32_32x32x16_bf16 v[16:31], v[234:237], v[222:225], v[16:31]
	s_cbranch_vccnz .LBB0_30
	s_add_i32 m0, s26, 0x8000
	s_add_i32 s6, s26, 0xa000
	global_load_lds_dwordx4 v[132:133], off
	s_mov_b32 m0, s26
	s_add_i32 s7, s26, 0x2000
	global_load_lds_dwordx4 v[134:135], off
	s_mov_b32 m0, s6
	s_nop 0
	global_load_lds_dwordx4 v[136:137], off
	s_mov_b32 m0, s7
	s_nop 0
	global_load_lds_dwordx4 v[138:139], off

; __device__ __forceinline__ int tid_fresh() { int t = threadIdx.x; asm volatile("" : "+v"(t)); return t; }
; __device__ __forceinline__ void gate_phase(int bx, int G, bool skip_ctx, const bf16* __restrict__ VG, const bf16* __restrict__ U, const float* __restrict__ stats, ...
;     const int tid = tid_fresh(), wid = tid >> 6, lane = tid & 63, r32 = lane & 31, hi = lane >> 5;
;     bf16* T = (bf16*)lds;
;     const int q = tid >> 2, dc = (tid & 3) * 16;
;     const int db = wid & 1, pb = wid >> 1, p = pb * 32 + r32;
;     const int NU = (M / 128) * 8;
;     auto unit_ok = [&](int u) { return u < NU && !(skip_ctx && ((u >> 3) % 34) < 2); };
;     auto next_unit = [&](int u) { u += G; while (u < NU && !unit_ok(u)) u += G; return u; };
;     int u = bx; if (!unit_ok(u)) u = next_unit(u);
;     GateRegs R;
;     ...
;     if (u < NU) GATE_LOAD(u);
;     ...
;             const float* gp = gsg + h * 64 + dc; const float* bp = bsg + h * 64 + dc;
;     ...
;         const float bias = bsl[h * 128 + p];
.LBB0_39:
	s_cmpk_gt_i32 s3, 0x87f
	s_cbranch_scc1 .LBB0_51
	s_lshl_b32 s22, s12, 9
	s_ashr_i32 s23, s22, 31
	s_lshl_b64 s[26:27], s[22:23], 2
	s_waitcnt lgkmcnt(0)
	s_add_u32 s22, s8, s26
	s_addc_u32 s23, s9, s27
	s_add_u32 s26, s10, s26
	s_addc_u32 s27, s11, s27
	s_ashr_i32 s13, s12, 31
	s_lshl_b64 s[8:9], s[12:13], 18
	s_add_u32 s8, s28, s8
	s_addc_u32 s9, s29, s9
	s_add_u32 s38, s8, 0x5800000
	s_addc_u32 s39, s9, 0
	s_lshl_b32 s8, s12, 10
	s_ashr_i32 s9, s8, 31
	s_lshl_b64 s[8:9], s[8:9], 2
	s_add_u32 s6, s6, s8
	s_addc_u32 s7, s7, s9
	v_ashrrev_i32_e32 v100, 2, v4
	s_movk_i32 s8, 0xffe0
	v_bfi_b32 v102, s8, v100, v4
	s_add_u32 s8, s28, 0x11efa000
	s_addc_u32 s9, s29, 0
	s_add_u32 s10, s28, 0x140fa000
	s_addc_u32 s11, s29, 0
	s_ashr_i32 s46, s3, 3
	s_ashr_i32 s47, s46, 31
	v_lshlrev_b32_e32 v0, 4, v4
	s_lshl_b64 s[46:47], s[46:47], 7
	v_ashrrev_i32_e32 v101, 31, v100
	v_and_b32_e32 v6, 48, v0
	v_lshl_add_u64 v[0:1], s[46:47], 0, v[100:101]
	s_and_b32 s13, s3, 7
	v_lshlrev_b64 v[2:3], 6, v[0:1]
	v_lshlrev_b64 v[0:1], 10, v[0:1]
	v_lshl_add_u64 v[0:1], s[10:11], 0, v[0:1]
	s_lshl_b32 s72, s13, 7
	v_lshl_add_u64 v[0:1], v[0:1], 0, s[72:73]
	v_lshlrev_b32_e32 v160, 1, v6
	v_lshl_add_u64 v[2:3], s[40:41], 0, v[2:3]
	v_lshl_add_u64 v[0:1], v[0:1], 0, v[160:161]
	v_ashrrev_i32_e32 v103, 31, v102
	global_load_dwordx4 v[16:19], v[2:3], off offset:48
	global_load_dwordx4 v[20:23], v[2:3], off offset:32
	global_load_dwordx4 v[24:27], v[2:3], off offset:16
	global_load_dwordx4 v[28:31], v[2:3], off
	global_load_dwordx4 v[32:35], v[0:1], off offset:16 nt
	global_load_dwordx4 v[36:39], v[0:1], off nt
	v_lshl_add_u64 v[0:1], s[46:47], 0, v[102:103]
	v_lshlrev_b64 v[0:1], 10, v[0:1]
	v_lshrrev_b32_e32 v2, 1, v4
	v_lshl_add_u64 v[0:1], s[8:9], 0, v[0:1]
	v_and_b32_e32 v8, 32, v2
	v_bfe_u32 v5, v4, 5, 1
	v_lshl_add_u64 v[0:1], v[0:1], 0, s[72:73]
	v_lshlrev_b32_e32 v160, 1, v8
	v_lshl_add_u64 v[0:1], v[0:1], 0, v[160:161]
	v_lshlrev_b32_e32 v160, 3, v5
	v_lshl_add_u64 v[0:1], v[0:1], 0, v[160:161]
	global_load_dwordx2 v[124:125], v[0:1], off nt
	global_load_dwordx2 v[122:123], v[0:1], off offset:16 nt
	global_load_dwordx2 v[120:121], v[0:1], off offset:32 nt
	global_load_dwordx2 v[106:107], v[0:1], off offset:48 nt
	v_lshl_add_u64 v[0:1], s[72:73], 0, v[102:103]
	v_lshlrev_b64 v[0:1], 8, v[0:1]
	v_lshl_add_u64 v[0:1], s[38:39], 0, v[0:1]
	v_lshlrev_b32_e32 v160, 4, v5
	v_lshl_add_u64 v[10:11], v[0:1], 0, v[160:161]
	global_load_dwordx4 v[0:3], v[10:11], off
	global_load_dwordx4 v[60:63], v[10:11], off offset:32
	global_load_dwordx4 v[64:67], v[10:11], off offset:64
	global_load_dwordx4 v[52:55], v[10:11], off offset:96
	global_load_dwordx4 v[56:59], v[10:11], off offset:128
	global_load_dwordx4 v[48:51], v[10:11], off offset:160
	global_load_dwordx4 v[44:47], v[10:11], off offset:192
	global_load_dwordx4 v[40:43], v[10:11], off offset:224
	v_lshlrev_b32_e32 v10, 2, v5
	v_lshlrev_b32_e32 v12, 2, v6
	v_mov_b32_e32 v13, v161
	v_and_or_b32 v4, v4, 31, v8
	s_movk_i32 s13, 0x110
	v_mul_u32_u24_e32 v9, 0x88, v6
	v_lshl_add_u64 v[104:105], s[22:23], 0, v[12:13]
	v_lshl_add_u64 v[108:109], s[26:27], 0, v[12:13]
	v_lshlrev_b32_e32 v5, 1, v100
	v_mad_u32_u24 v7, v4, s13, 0
	v_or_b32_e32 v4, v10, v8
	v_lshlrev_b64 v[12:13], 11, v[102:103]
	v_lshlrev_b32_e32 v9, 1, v9
	v_lshl_add_u64 v[110:111], s[38:39], 0, v[160:161]
	v_lshl_add_u64 v[112:113], s[16:17], 0, v[12:13]
	v_add3_u32 v134, 0, v5, v9
	v_add3_u32 v135, 0, v9, v5
	v_lshlrev_b32_e32 v114, 1, v6
	v_lshlrev_b32_e32 v116, 1, v8
	v_lshlrev_b32_e32 v118, 1, v10
	v_add_u32_e32 v136, v7, v160
	v_lshlrev_b32_e32 v160, 1, v4
	s_and_b32 s37, s3, 7
	s_lshl_b32 s38, s37, 8
	s_mov_b32 s39, 0
	v_lshl_add_u64 v[252:253], v[104:105], 0, s[38:39]
	global_load_dwordx4 v[218:221], v[252:253], off
	global_load_dwordx4 v[222:225], v[252:253], off offset:16
	global_load_dwordx4 v[226:229], v[252:253], off offset:32
	global_load_dwordx4 v[230:233], v[252:253], off offset:48
	v_lshl_add_u64 v[252:253], v[108:109], 0, s[38:39]
	global_load_dwordx4 v[234:237], v[252:253], off
	global_load_dwordx4 v[238:241], v[252:253], off offset:16
	global_load_dwordx4 v[242:245], v[252:253], off offset:32
	global_load_dwordx4 v[246:249], v[252:253], off offset:48
	v_lshl_add_u32 v252, s37, 7, v102
	v_ashrrev_i32_e32 v253, 31, v252
	v_lshl_add_u64 v[252:253], v[252:253], 2, s[6:7]
	global_load_dword v137, v[252:253], off
	s_branch .LBB0_45

; __device__ __forceinline__ unsigned pk2(float lo, float hi) { return pg8::cvt_pk_bf16(lo, hi); }
; __device__ __forceinline__ float bflo(unsigned w) { return __uint_as_float(w << 16); }
; __device__ __forceinline__ float bfhi(unsigned w) { return __uint_as_float(w & 0xffff0000u); }
; __device__ __forceinline__ void gate_phase(int bx, int G, bool skip_ctx, const bf16* __restrict__ VG, const bf16* __restrict__ U, const float* __restrict__ stats, ...
;     ...
;         __syncthreads();
;         f32x16 acc = {};
;         const bf16* trow = T + (db * 32 + r32) * GT_PITCH + hi * 8;
; #pragma unroll
;         for (int ks = 0; ks < 8; ++ks) {
;             const bf16x8 av = *(const bf16x8*)(trow + ks * 16);
;             acc = __builtin_amdgcn_mfma_f32_32x32x16_bf16(av, wcur[ks], acc, 0, 0, 0);
;         }
;         const size_t row = (size_t)chunk * 128 + p;
; #pragma unroll
;         for (int g4 = 0; g4 < 4; ++g4) {
;             const int d0 = db * 32 + 8 * g4 + 4 * hi;
;             u32x2 w;
;             w.x = pk2(bflo(ucur[g4].x) * (acc[4 * g4 + 0] + bias), bfhi(ucur[g4].x) * (acc[4 * g4 + 1] + bias));
;             w.y = pk2(bflo(ucur[g4].y) * (acc[4 * g4 + 2] + bias), bfhi(ucur[g4].y) * (acc[4 * g4 + 3] + bias));
;             *(u32x2*)(MIX + row * 1024 + 512 + h * 64 + d0) = w;
;         }
;         __syncthreads();
;         u = un;
.LBB0_44:
	s_waitcnt lgkmcnt(0)
	s_barrier
	ds_read_b128 v[4:7], v136
	ds_read_b128 v[138:141], v136 offset:32
	s_waitcnt lgkmcnt(1)
	v_mfma_f32_32x32x16_bf16 v[0:15], v[4:7], v[0:3], 0
	s_ashr_i32 s26, s13, 3
	s_ashr_i32 s27, s26, 31
	s_lshl_b64 s[26:27], s[26:27], 18
	s_lshl_b32 s72, s19, 1
	s_andn2_b64 vcc, exec, s[22:23]
	s_waitcnt lgkmcnt(0)
	v_mfma_f32_32x32x16_bf16 v[0:15], v[138:141], v[60:63], v[0:15]
	ds_read_b128 v[60:63], v136 offset:64
	s_waitcnt lgkmcnt(0)
	v_mfma_f32_32x32x16_bf16 v[0:15], v[60:63], v[64:67], v[0:15]
	ds_read_b128 v[60:63], v136 offset:96
	v_mov_b64_e32 v[64:65], v[76:77]
	v_mov_b64_e32 v[66:67], v[78:79]
	s_waitcnt lgkmcnt(0)
	v_mfma_f32_32x32x16_bf16 v[0:15], v[60:63], v[52:55], v[0:15]
	ds_read_b128 v[52:55], v136 offset:128
	v_mov_b64_e32 v[60:61], v[72:73]
	v_mov_b64_e32 v[62:63], v[74:75]
	s_waitcnt lgkmcnt(0)
	v_mfma_f32_32x32x16_bf16 v[0:15], v[52:55], v[56:59], v[0:15]
	ds_read_b128 v[52:55], v136 offset:160
	v_mov_b64_e32 v[56:57], v[84:85]
	v_mov_b64_e32 v[58:59], v[86:87]
	s_waitcnt lgkmcnt(0)
	v_mfma_f32_32x32x16_bf16 v[0:15], v[52:55], v[48:51], v[0:15]
	ds_read_b128 v[48:51], v136 offset:192
	v_mov_b64_e32 v[52:53], v[80:81]
	v_mov_b64_e32 v[54:55], v[82:83]
	s_waitcnt lgkmcnt(0)
	v_mfma_f32_32x32x16_bf16 v[0:15], v[48:51], v[44:47], v[0:15]
	ds_read_b128 v[44:47], v136 offset:224
	v_mov_b64_e32 v[48:49], v[88:89]
	v_mov_b64_e32 v[50:51], v[90:91]
	s_waitcnt lgkmcnt(0)
	v_mfma_f32_32x32x16_bf16 v[0:15], v[44:47], v[40:43], v[0:15]
	v_lshlrev_b32_e32 v42, 16, v124
	v_lshl_add_u64 v[40:41], v[112:113], 0, s[26:27]
	v_lshl_add_u64 v[40:41], v[40:41], 0, s[72:73]
	v_mov_b64_e32 v[44:45], v[92:93]
	v_mov_b64_e32 v[46:47], v[94:95]
	s_nop 10
	v_add_f32_e32 v0, v137, v0
	v_mul_f32_e32 v0, v0, v42
	v_and_b32_e32 v42, 0xffff0000, v124
	v_add_f32_e32 v1, v137, v1
	v_mul_f32_e32 v1, v1, v42
	v_cvt_pk_bf16_f32 v42, v0, v1
	v_lshlrev_b32_e32 v0, 16, v125
	v_add_f32_e32 v1, v137, v2
	v_mul_f32_e32 v0, v1, v0
	v_and_b32_e32 v1, 0xffff0000, v125
	v_add_f32_e32 v2, v137, v3
	v_mul_f32_e32 v1, v2, v1
	v_lshlrev_b32_e32 v2, 16, v122
	v_add_f32_e32 v3, v137, v4
	v_mul_f32_e32 v2, v3, v2
	v_and_b32_e32 v3, 0xffff0000, v122
	v_add_f32_e32 v4, v137, v5
	v_cvt_pk_bf16_f32 v43, v0, v1
	v_lshl_add_u64 v[0:1], v[40:41], 0, v[160:161]
	v_mul_f32_e32 v3, v4, v3
	global_store_dwordx2 v[0:1], v[42:43], off offset:1024
	v_cvt_pk_bf16_f32 v2, v2, v3
	v_lshlrev_b32_e32 v3, 16, v123
	v_add_f32_e32 v4, v137, v6
	v_mul_f32_e32 v3, v4, v3
	v_and_b32_e32 v4, 0xffff0000, v123
	v_add_f32_e32 v5, v137, v7
	v_mul_f32_e32 v4, v5, v4
	v_cvt_pk_bf16_f32 v3, v3, v4
	global_store_dwordx2 v[0:1], v[2:3], off offset:1040
	v_lshlrev_b32_e32 v2, 16, v120
	v_add_f32_e32 v3, v137, v8
	v_mul_f32_e32 v2, v3, v2
	v_and_b32_e32 v3, 0xffff0000, v120
	v_add_f32_e32 v4, v137, v9
	v_mul_f32_e32 v3, v4, v3
	v_cvt_pk_bf16_f32 v2, v2, v3
	v_lshlrev_b32_e32 v3, 16, v121
	v_add_f32_e32 v4, v137, v10
	v_mul_f32_e32 v3, v4, v3
	v_and_b32_e32 v4, 0xffff0000, v121
	v_add_f32_e32 v5, v137, v11
	v_mul_f32_e32 v4, v5, v4
	v_cvt_pk_bf16_f32 v3, v3, v4
	global_store_dwordx2 v[0:1], v[2:3], off offset:1056
	v_lshlrev_b32_e32 v2, 16, v106
	v_add_f32_e32 v3, v137, v12
	v_mul_f32_e32 v2, v3, v2
	v_and_b32_e32 v3, 0xffff0000, v106
	v_add_f32_e32 v4, v137, v13
	v_mul_f32_e32 v3, v4, v3
	v_cvt_pk_bf16_f32 v2, v2, v3
	v_lshlrev_b32_e32 v3, 16, v107
	v_add_f32_e32 v4, v137, v14
	v_mul_f32_e32 v3, v4, v3
	v_and_b32_e32 v4, 0xffff0000, v107
	v_add_f32_e32 v5, v137, v15
	v_mul_f32_e32 v4, v5, v4
	v_cvt_pk_bf16_f32 v3, v3, v4
	global_store_dwordx2 v[0:1], v[2:3], off offset:1072
	s_waitcnt vmcnt(4)
	v_mov_b64_e32 v[0:1], v[68:69]
	v_mov_b64_e32 v[40:41], v[96:97]
	v_mov_b64_e32 v[124:125], v[126:127]
	v_mov_b64_e32 v[122:123], v[128:129]
	v_mov_b64_e32 v[120:121], v[130:131]
	v_mov_b64_e32 v[106:107], v[132:133]
	v_mov_b64_e32 v[2:3], v[70:71]
	v_mov_b64_e32 v[42:43], v[98:99]
	s_barrier
	s_cbranch_vccnz .LBB0_51
; __device__ __forceinline__ unsigned f2bf(float f) { unsigned u = __builtin_bit_cast(unsigned, f); return (u + 0x7fffu + ((u >> 16) & 1u)) >> 16; }
; __device__ __forceinline__ float bflo(unsigned w) { return __uint_as_float(w << 16); }
; __device__ __forceinline__ float bfhi(unsigned w) { return __uint_as_float(w & 0xffff0000u); }
; __device__ __forceinline__ void gate_phase(int bx, int G, bool skip_ctx, const bf16* __restrict__ VG, const bf16* __restrict__ U, const float* __restrict__ stats, ...
;     ...
;     while (u < NU) {
;         const int chunk = u >> 3, h = u & 7;
;         {
;             const float s1 = (R.sa[0] + R.sa[2]) + (R.sb[0] + R.sb[2]) + (R.sc[0] + R.sc[2]) + (R.sd[0] + R.sd[2]);
;             const float s2 = (R.sa[1] + R.sa[3]) + (R.sb[1] + R.sb[3]) + (R.sc[1] + R.sc[3]) + (R.sd[1] + R.sd[3]);
;             const float mean = s1 * (1.0f / 512.0f);
;             const float var = fmaxf(s2 * (1.0f / 512.0f) - mean * mean, 0.f);
;             const float rstd = __builtin_amdgcn_rsqf(var + EPS);
;             const float* gp = gsg + h * 64 + dc; const float* bp = bsg + h * 64 + dc;
; #pragma unroll
;             for (int i = 0; i < 8; ++i) {
;                 const unsigned w = i < 4 ? R.v0[i] : R.v1[i - 4];
;                 const float x0 = (bflo(w) - mean) * rstd * gp[2 * i] + bp[2 * i], x1 = (bfhi(w) - mean) * rstd * gp[2 * i + 1] + bp[2 * i + 1];
;                 T[(dc + 2 * i) * GT_PITCH + q] = (bf16)f2bf(x0); T[(dc + 2 * i + 1) * GT_PITCH + q] = (bf16)f2bf(x1);
;             }
;         }
.LBB0_45:
	s_and_b32 s22, s3, 7
	s_lshl_b32 s72, s22, 8
	s_waitcnt vmcnt(23)
	v_add_f32_e32 v82, v28, v30
	v_add_f32_e32 v83, v24, v26
	v_add_f32_e32 v88, v29, v31
	v_add_f32_e32 v89, v25, v27
	v_add_f32_e32 v86, v20, v22
	v_add_f32_e32 v90, v21, v23
	v_add_f32_e32 v82, v83, v82
	v_add_f32_e32 v83, v89, v88
	v_add_f32_e32 v87, v16, v18
	v_add_f32_e32 v91, v17, v19
	v_add_f32_e32 v82, v86, v82
	v_add_f32_e32 v83, v90, v83
	v_add_f32_e32 v90, v87, v82
	v_add_f32_e32 v91, v91, v83
	s_nop 0
	v_mul_f32_e32 v115, 0x3b000000, v90
	s_lshl_b32 s19, s22, 6
	v_mul_f32_e32 v115, v115, v115
	s_mov_b32 s22, 0x3b000000
	v_fma_f32 v91, v91, s22, -v115
	v_max_f32_e32 v91, 0, v91
	v_add_f32_e32 v91, 0x358637bd, v91
	v_rsq_f32_e32 v91, v91
	s_waitcnt vmcnt(21)
	v_lshlrev_b32_e32 v92, 16, v36
	v_lshlrev_b32_e32 v94, 16, v37
	v_lshlrev_b32_e32 v96, 16, v38
	v_and_b32_e32 v93, 0xffff0000, v36
	v_and_b32_e32 v95, 0xffff0000, v37
	v_and_b32_e32 v97, 0xffff0000, v38
	v_fmac_f32_e32 v92, 0xbb000000, v90
	v_fmac_f32_e32 v94, 0xbb000000, v90
	v_fmac_f32_e32 v96, 0xbb000000, v90
	v_lshlrev_b32_e32 v98, 16, v39
	v_fmac_f32_e32 v93, 0xbb000000, v90
	v_fmac_f32_e32 v95, 0xbb000000, v90
	v_fmac_f32_e32 v97, 0xbb000000, v90
	v_mul_f32_e32 v88, v92, v91
	v_mul_f32_e32 v92, v94, v91
	v_mul_f32_e32 v94, v96, v91
	v_fmac_f32_e32 v98, 0xbb000000, v90
	v_mul_f32_e32 v89, v93, v91
	v_mul_f32_e32 v93, v95, v91
	v_mul_f32_e32 v95, v97, v91
	v_and_b32_e32 v99, 0xffff0000, v39
	v_mul_f32_e32 v96, v98, v91
	v_fmac_f32_e32 v99, 0xbb000000, v90
	v_mul_f32_e32 v97, v99, v91
	s_mov_b32 s13, s3
	s_waitcnt vmcnt(0)
	v_fma_f32 v68, v88, v218, v234
	v_fma_f32 v69, v89, v219, v235
	v_fma_f32 v12, v94, v222, v238
	v_fma_f32 v70, v92, v220, v236
	v_fma_f32 v71, v93, v221, v237
	v_fma_f32 v13, v95, v223, v239
	v_bfe_u32 v72, v68, 16, 1
	v_bfe_u32 v76, v12, 16, 1
	v_fma_f32 v14, v96, v224, v240
	v_bfe_u32 v73, v69, 16, 1
	v_bfe_u32 v74, v70, 16, 1
	v_bfe_u32 v75, v71, 16, 1
	v_bfe_u32 v77, v13, 16, 1
	v_add3_u32 v68, v68, v72, s56
	v_add3_u32 v12, v12, v76, s56
	v_add3_u32 v69, v69, v73, s56
	v_add3_u32 v70, v70, v74, s56
	v_add3_u32 v71, v71, v75, s56
	v_add3_u32 v13, v13, v77, s56
	ds_write_b16_d16_hi v134, v68
	ds_write_b16_d16_hi v135, v69 offset:272
	ds_write_b16_d16_hi v134, v70 offset:544
	ds_write_b16_d16_hi v135, v71 offset:816
	ds_write_b16_d16_hi v134, v12 offset:1088
	ds_write_b16_d16_hi v135, v13 offset:1360
	v_bfe_u32 v12, v14, 16, 1
	v_fma_f32 v15, v97, v225, v241
	v_add3_u32 v12, v14, v12, s56
	ds_write_b16_d16_hi v134, v12 offset:1632
	v_bfe_u32 v12, v15, 16, 1
	v_add3_u32 v12, v15, v12, s56
	ds_write_b16_d16_hi v135, v12 offset:1904
	v_lshlrev_b32_e32 v12, 16, v32
	v_fmac_f32_e32 v12, 0xbb000000, v90
	v_mul_f32_e32 v12, v12, v91
	v_fma_f32 v4, v12, v226, v242
	v_and_b32_e32 v8, 0xffff0000, v32
	v_fmac_f32_e32 v8, 0xbb000000, v90
	v_mul_f32_e32 v8, v8, v91
	v_fma_f32 v5, v8, v227, v243
	v_bfe_u32 v8, v4, 16, 1
	v_add3_u32 v4, v4, v8, s56
	ds_write_b16_d16_hi v134, v4 offset:2176
	v_bfe_u32 v4, v5, 16, 1
	v_add3_u32 v4, v5, v4, s56
	ds_write_b16_d16_hi v135, v4 offset:2448
	v_lshlrev_b32_e32 v4, 16, v33
	v_fmac_f32_e32 v4, 0xbb000000, v90
	v_and_b32_e32 v5, 0xffff0000, v33
	v_mul_f32_e32 v4, v4, v91
	v_fmac_f32_e32 v5, 0xbb000000, v90
	v_fma_f32 v4, v4, v228, v244
	v_mul_f32_e32 v5, v5, v91
	v_fma_f32 v7, v5, v229, v245
	v_bfe_u32 v5, v4, 16, 1
	v_add3_u32 v4, v4, v5, s56
	ds_write_b16_d16_hi v134, v4 offset:2720
	v_bfe_u32 v4, v7, 16, 1
	v_add3_u32 v4, v7, v4, s56
	ds_write_b16_d16_hi v135, v4 offset:2992
	v_lshlrev_b32_e32 v4, 16, v34
	v_fmac_f32_e32 v4, 0xbb000000, v90
	v_mul_f32_e32 v4, v4, v91
	v_and_b32_e32 v5, 0xffff0000, v34
	v_fma_f32 v4, v4, v230, v246
	v_fmac_f32_e32 v5, 0xbb000000, v90
	v_mul_f32_e32 v5, v5, v91
	v_bfe_u32 v6, v4, 16, 1
	v_fma_f32 v5, v5, v231, v247
	v_add3_u32 v4, v4, v6, s56
	ds_write_b16_d16_hi v134, v4 offset:3264
	v_bfe_u32 v4, v5, 16, 1
	v_add3_u32 v4, v5, v4, s56
	ds_write_b16_d16_hi v135, v4 offset:3536
	v_lshlrev_b32_e32 v4, 16, v35
	v_fmac_f32_e32 v4, 0xbb000000, v90
	v_and_b32_e32 v5, 0xffff0000, v35
	v_mul_f32_e32 v4, v4, v91
	v_fmac_f32_e32 v5, 0xbb000000, v90
	v_fma_f32 v4, v4, v232, v248
	v_mul_f32_e32 v5, v5, v91
	v_fma_f32 v87, v5, v233, v249
	v_bfe_u32 v5, v4, 16, 1
	v_add3_u32 v4, v4, v5, s56
	ds_write_b16_d16_hi v134, v4 offset:3808
	v_bfe_u32 v4, v87, 16, 1
	v_add3_u32 v4, v87, v4, s56
	ds_write_b16_d16_hi v135, v4 offset:4080
	s_branch .LBB0_47

; __device__ __forceinline__ void gate_phase(int bx, int G, bool skip_ctx, const bf16* __restrict__ VG, const bf16* __restrict__ U, const float* __restrict__ stats, ...
;     ...
;         u32x2 ucur[4]; bf16x8 wcur[8];
; #pragma unroll
;         for (int g4 = 0; g4 < 4; ++g4) ucur[g4] = R.uu[g4];
; #pragma unroll
;         for (int ks = 0; ks < 8; ++ks) wcur[ks] = R.wf[ks];
;         const float bias = bsl[h * 128 + p];
;         const int un = next_unit(u);
;         if (un < NU) GATE_LOAD(un);
.LBB0_49:
	v_mov_b64_e32 v[70:71], v[2:3]
	v_mov_b64_e32 v[74:75], v[62:63]
	v_mov_b64_e32 v[78:79], v[66:67]
	v_mov_b64_e32 v[82:83], v[54:55]
	v_mov_b64_e32 v[86:87], v[58:59]
	v_mov_b64_e32 v[90:91], v[50:51]
	v_mov_b64_e32 v[94:95], v[46:47]
	v_mov_b64_e32 v[98:99], v[42:43]
	s_mov_b64 s[22:23], 0
	s_andn2_b64 vcc, exec, s[38:39]
	v_mov_b64_e32 v[126:127], v[124:125]
	v_mov_b64_e32 v[128:129], v[122:123]
	v_mov_b64_e32 v[130:131], v[120:121]
	v_mov_b64_e32 v[132:133], v[106:107]
	v_mov_b64_e32 v[68:69], v[0:1]
	v_mov_b64_e32 v[72:73], v[60:61]
	v_mov_b64_e32 v[76:77], v[64:65]
	v_mov_b64_e32 v[80:81], v[52:53]
	v_mov_b64_e32 v[84:85], v[56:57]
	v_mov_b64_e32 v[88:89], v[48:49]
	v_mov_b64_e32 v[92:93], v[44:45]
	v_mov_b64_e32 v[96:97], v[40:41]
	s_cbranch_vccz .LBB0_44
	s_ashr_i32 s27, s26, 31
	s_lshl_b64 s[22:23], s[26:27], 7
	v_lshl_add_u64 v[4:5], s[22:23], 0, v[100:101]
	s_and_b32 s25, s3, 7
	v_lshlrev_b64 v[6:7], 6, v[4:5]
	v_lshlrev_b64 v[4:5], 10, v[4:5]
	v_lshl_add_u64 v[4:5], s[10:11], 0, v[4:5]
	s_lshl_b32 s72, s25, 7
	v_lshl_add_u64 v[4:5], v[4:5], 0, s[72:73]
	v_mov_b32_e32 v115, v161
	v_lshl_add_u64 v[6:7], s[40:41], 0, v[6:7]
	v_lshl_add_u64 v[4:5], v[4:5], 0, v[114:115]
	global_load_dwordx4 v[16:19], v[6:7], off offset:48
	global_load_dwordx4 v[20:23], v[6:7], off offset:32
	global_load_dwordx4 v[24:27], v[6:7], off offset:16
	global_load_dwordx4 v[28:31], v[6:7], off
	global_load_dwordx4 v[32:35], v[4:5], off offset:16 nt
	global_load_dwordx4 v[36:39], v[4:5], off nt
	v_lshl_add_u64 v[4:5], s[22:23], 0, v[102:103]
	v_lshlrev_b64 v[4:5], 10, v[4:5]
	v_lshl_add_u64 v[4:5], s[8:9], 0, v[4:5]
	v_lshl_add_u64 v[4:5], v[4:5], 0, s[72:73]
	v_mov_b32_e32 v117, v161
	v_lshl_add_u64 v[4:5], v[4:5], 0, v[116:117]
	v_mov_b32_e32 v119, v161
	v_lshl_add_u64 v[4:5], v[4:5], 0, v[118:119]
	global_load_dwordx2 v[126:127], v[4:5], off nt
	global_load_dwordx2 v[128:129], v[4:5], off offset:16 nt
	global_load_dwordx2 v[130:131], v[4:5], off offset:32 nt
	global_load_dwordx2 v[132:133], v[4:5], off offset:48 nt
	v_lshl_add_u64 v[4:5], s[72:73], 0, v[102:103]
	v_lshlrev_b64 v[4:5], 8, v[4:5]
	v_lshl_add_u64 v[4:5], v[110:111], 0, v[4:5]
	s_mov_b64 s[22:23], -1
	s_branch .LBB0_44
